# P17 fused epilogue: row halves pipelined (statistics of rows 0-127 published after the second quarter, exchange overlapped with quarters 3-4 and with the output stores of the first half); cooperative
# baseline (speedup 1.0000x reference)
.LBB0_1984:
	v_lshlrev_b32_e32 v130, 3, v153
	v_and_b32_e32 v190, 0x78, v130
	v_ashrrev_i32_e32 v152, 4, v153
	v_lshrrev_b32_e32 v130, 1, v153
	v_and_b32_e32 v191, 0x60, v130
	v_or_b32_e32 v130, 4, v190
	v_lshlrev_b32_e32 v132, 2, v152
	v_bitop3_b32 v133, v132, v190, 48 bitop3:0x6c
	v_bitop3_b32 v132, v132, v130, 48 bitop3:0x6c
	v_lshlrev_b32_e32 v134, 9, v152
	v_lshlrev_b32_e32 v132, 2, v132
	v_add_u32_e32 v151, 32, v152
	v_lshlrev_b32_e32 v133, 2, v133
	v_add3_u32 v148, s44, v132, v134
	v_lshlrev_b32_e32 v132, 2, v151
	v_add3_u32 v147, s44, v133, v134
	v_bitop3_b32 v133, v132, v190, 48 bitop3:0x6c
	v_bitop3_b32 v132, v132, v130, 48 bitop3:0x6c
	v_lshlrev_b32_e32 v134, 9, v151
	v_lshlrev_b32_e32 v132, 2, v132
	v_add_u32_e32 v150, 64, v152
	v_lshlrev_b32_e32 v133, 2, v133
	v_add3_u32 v145, s44, v132, v134
	v_lshlrev_b32_e32 v132, 2, v150
	v_add3_u32 v146, s44, v133, v134
	v_bitop3_b32 v133, v132, v190, 48 bitop3:0x6c
	v_bitop3_b32 v132, v132, v130, 48 bitop3:0x6c
	v_lshlrev_b32_e32 v134, 9, v150
	v_lshlrev_b32_e32 v132, 2, v132
	v_add_u32_e32 v149, 0x60, v152
	v_lshlrev_b32_e32 v133, 2, v133
	v_add3_u32 v143, s44, v132, v134
	v_lshlrev_b32_e32 v132, 2, v149
	v_add3_u32 v144, s44, v133, v134
	v_bitop3_b32 v133, v132, v190, 48 bitop3:0x6c
	v_bitop3_b32 v130, v132, v130, 48 bitop3:0x6c
	v_lshlrev_b32_e32 v133, 2, v133
	v_lshlrev_b32_e32 v134, 9, v149
	v_lshlrev_b32_e32 v130, 2, v130
	s_lshl_b64 s[38:39], s[36:37], 2
	v_add3_u32 v141, s44, v133, v134
	v_add3_u32 v140, s44, v130, v134
	v_bfe_u32 v189, v153, 4, 2
	v_and_b32_e32 v188, 15, v153
	v_lshlrev_b32_e32 v193, 4, v189
	v_lshlrev_b32_e32 v153, 7, v153
	v_or_b32_e32 v192, v191, v188
	v_bitop3_b32 v188, v191, v193, v188 bitop3:0x36
	v_and_b32_e32 v153, 0xffff8000, v153
	v_lshlrev_b32_e32 v188, 2, v188
	v_lshl_or_b32 v189, v189, 11, v153
	v_add3_u32 v153, s44, v188, v189
	v_bitop3_b32 v252, v192, v193, 16 bitop3:0x36
	v_lshlrev_b32_e32 v252, 2, v252
	v_add3_u32 v252, s44, v252, v189
	v_lshrrev_b32_e32 v149, 4, v0
	v_add_u32_e32 v236, s49, v149
	v_lshlrev_b32_e32 v149, 3, v149
	v_and_b32_e32 v152, 15, v0
	v_lshlrev_b32_e32 v152, 5, v152
	s_lshl_b32 s2, s36, 2
	v_add_u32_e32 v152, s2, v152
	v_mov_b32_e32 v225, 0
	v_mov_b32_e32 v224, v236
	v_lshlrev_b64 v[224:225], 12, v[224:225]
	v_mov_b32_e32 v226, v152
	v_mov_b32_e32 v227, 0
	v_lshl_add_u64 v[224:225], v[224:225], 0, v[226:227]
	v_lshl_add_u64 v[226:227], s[66:67], 0, v[224:225]
	s_lshl_b32 s2, s49, 3
	s_add_u32 s12, s62, 0xf000000
	s_addc_u32 s13, s63, 0
	s_add_u32 s12, s12, s2
	s_addc_u32 s13, s13, 0
	v_readlane_b32 s14, v253, 46
	v_readlane_b32 s15, v253, 47
	v_readlane_b32 s16, v255, 40
	v_readlane_b32 s17, v255, 41
	s_mov_b32 s4, 0x20000
	s_mov_b32 s5, 0
	s_mov_b32 s11, 0
	s_lshr_b32 s2, s49, 8
	s_lshl_b32 s3, s2, 13
	s_add_u32 s18, s62, 0xf100000
	s_addc_u32 s19, s63, 0
	s_add_u32 s18, s18, s3
	s_addc_u32 s19, s19, 0
	s_lshl_b32 s3, s2, 2
	s_add_u32 s20, s62, 0xf71a000
	s_addc_u32 s21, s63, 0
	s_add_u32 s20, s20, s3
	s_addc_u32 s21, s21, 0
	s_add_u32 s22, s20, 0x100
	s_addc_u32 s23, s21, 0
	s_lshr_b32 s2, s36, 8
	s_lshl_b32 s2, s2, 11
	v_add_u32_e32 v1, s2, v149
	s_mov_b32 s10, 0x0
	v_lshl_add_u64 v[150:151], v[226:227], 0, s[10:11]
	v_lshl_add_u64 v[218:219], v[150:151], 0, s[4:5]
	v_lshl_add_u64 v[220:221], v[218:219], 0, s[4:5]
	v_lshl_add_u64 v[222:223], v[220:221], 0, s[4:5]
	global_load_dwordx2 v[138:139], v149, s[12:13] offset:0
	global_load_dwordx2 v[246:247], v149, s[12:13] offset:256
	global_load_dwordx2 v[248:249], v149, s[12:13] offset:512
	global_load_dwordx2 v[250:251], v149, s[12:13] offset:768
	global_load_dwordx4 v[130:133], v152, s[14:15] offset:0
	global_load_dwordx4 v[134:137], v152, s[14:15] offset:16
	global_load_dwordx4 v[238:241], v152, s[16:17] offset:0
	global_load_dwordx4 v[242:245], v152, s[16:17] offset:16
	global_load_dwordx4 v[186:189], v[150:151], off
	global_load_dwordx4 v[190:193], v[150:151], off offset:16
	global_load_dwordx4 v[194:197], v[218:219], off
	global_load_dwordx4 v[198:201], v[218:219], off offset:16
	global_load_dwordx4 v[202:205], v[220:221], off
	global_load_dwordx4 v[206:209], v[220:221], off offset:16
	global_load_dwordx4 v[210:213], v[222:223], off
	global_load_dwordx4 v[214:217], v[222:223], off offset:16
	ds_write2st64_b32 v153, v126, v127 offset1:2
	ds_write2st64_b32 v153, v128, v129 offset0:4 offset1:6
	ds_write2st64_b32 v252, v98, v99 offset1:2
	ds_write2st64_b32 v252, v100, v101 offset0:4 offset1:6
	ds_write2st64_b32 v153, v102, v103 offset0:32 offset1:34
	ds_write2st64_b32 v153, v104, v105 offset0:36 offset1:38
	ds_write2st64_b32 v252, v106, v107 offset0:32 offset1:34
	ds_write2st64_b32 v252, v108, v109 offset0:36 offset1:38
	ds_write2st64_b32 v153, v110, v111 offset0:64 offset1:66
	ds_write2st64_b32 v153, v112, v113 offset0:68 offset1:70
	ds_write2st64_b32 v252, v114, v115 offset0:64 offset1:66
	ds_write2st64_b32 v252, v116, v117 offset0:68 offset1:70
	ds_write2st64_b32 v153, v118, v119 offset0:96 offset1:98
	ds_write2st64_b32 v153, v120, v121 offset0:100 offset1:102
	ds_write2st64_b32 v252, v122, v123 offset0:96 offset1:98
	ds_write2st64_b32 v252, v124, v125 offset0:100 offset1:102
	s_waitcnt lgkmcnt(0)
	s_barrier
	ds_read_b128 v[154:157], v147
	ds_read_b128 v[158:161], v148
	ds_read_b128 v[162:165], v146
	ds_read_b128 v[166:169], v145
	ds_read_b128 v[170:173], v144
	ds_read_b128 v[174:177], v143
	ds_read_b128 v[178:181], v141
	ds_read_b128 v[182:185], v140
	s_waitcnt vmcnt(0) lgkmcnt(0)
	s_barrier
	v_pk_add_f32 v[186:187], v[186:187], v[138:139] op_sel_hi:[1,0] neg_lo:[0,1] neg_hi:[0,1]
	v_pk_mul_f32 v[186:187], v[186:187], v[138:139] op_sel:[0,1]
	v_pk_fma_f32 v[186:187], v[130:131], v[186:187], v[238:239]
	v_pk_fma_f32 v[98:99], v[186:187], s[30:31], v[154:155] op_sel_hi:[1,0,1]
	v_pk_add_f32 v[188:189], v[188:189], v[138:139] op_sel_hi:[1,0] neg_lo:[0,1] neg_hi:[0,1]
	v_pk_mul_f32 v[188:189], v[188:189], v[138:139] op_sel:[0,1]
	v_pk_fma_f32 v[188:189], v[132:133], v[188:189], v[240:241]
	v_pk_fma_f32 v[100:101], v[188:189], s[30:31], v[156:157] op_sel_hi:[1,0,1]
	v_pk_add_f32 v[190:191], v[190:191], v[138:139] op_sel_hi:[1,0] neg_lo:[0,1] neg_hi:[0,1]
	v_pk_mul_f32 v[190:191], v[190:191], v[138:139] op_sel:[0,1]
	v_pk_fma_f32 v[190:191], v[134:135], v[190:191], v[242:243]
	v_pk_fma_f32 v[102:103], v[190:191], s[30:31], v[158:159] op_sel_hi:[1,0,1]
	v_pk_add_f32 v[192:193], v[192:193], v[138:139] op_sel_hi:[1,0] neg_lo:[0,1] neg_hi:[0,1]
	v_pk_mul_f32 v[192:193], v[192:193], v[138:139] op_sel:[0,1]
	v_pk_fma_f32 v[192:193], v[136:137], v[192:193], v[244:245]
	v_pk_fma_f32 v[104:105], v[192:193], s[30:31], v[160:161] op_sel_hi:[1,0,1]
	v_pk_add_f32 v[194:195], v[194:195], v[246:247] op_sel_hi:[1,0] neg_lo:[0,1] neg_hi:[0,1]
	v_pk_mul_f32 v[194:195], v[194:195], v[246:247] op_sel:[0,1]
	v_pk_fma_f32 v[194:195], v[130:131], v[194:195], v[238:239]
	v_pk_fma_f32 v[106:107], v[194:195], s[30:31], v[162:163] op_sel_hi:[1,0,1]
	v_pk_add_f32 v[196:197], v[196:197], v[246:247] op_sel_hi:[1,0] neg_lo:[0,1] neg_hi:[0,1]
	v_pk_mul_f32 v[196:197], v[196:197], v[246:247] op_sel:[0,1]
	v_pk_fma_f32 v[196:197], v[132:133], v[196:197], v[240:241]
	v_pk_fma_f32 v[108:109], v[196:197], s[30:31], v[164:165] op_sel_hi:[1,0,1]
	v_pk_add_f32 v[198:199], v[198:199], v[246:247] op_sel_hi:[1,0] neg_lo:[0,1] neg_hi:[0,1]
	v_pk_mul_f32 v[198:199], v[198:199], v[246:247] op_sel:[0,1]
	v_pk_fma_f32 v[198:199], v[134:135], v[198:199], v[242:243]
	v_pk_fma_f32 v[110:111], v[198:199], s[30:31], v[166:167] op_sel_hi:[1,0,1]
	v_pk_add_f32 v[200:201], v[200:201], v[246:247] op_sel_hi:[1,0] neg_lo:[0,1] neg_hi:[0,1]
	v_pk_mul_f32 v[200:201], v[200:201], v[246:247] op_sel:[0,1]
	v_pk_fma_f32 v[200:201], v[136:137], v[200:201], v[244:245]
	v_pk_fma_f32 v[112:113], v[200:201], s[30:31], v[168:169] op_sel_hi:[1,0,1]
	v_pk_add_f32 v[202:203], v[202:203], v[248:249] op_sel_hi:[1,0] neg_lo:[0,1] neg_hi:[0,1]
	v_pk_mul_f32 v[202:203], v[202:203], v[248:249] op_sel:[0,1]
	v_pk_fma_f32 v[202:203], v[130:131], v[202:203], v[238:239]
	v_pk_fma_f32 v[114:115], v[202:203], s[30:31], v[170:171] op_sel_hi:[1,0,1]
	v_pk_add_f32 v[204:205], v[204:205], v[248:249] op_sel_hi:[1,0] neg_lo:[0,1] neg_hi:[0,1]
	v_pk_mul_f32 v[204:205], v[204:205], v[248:249] op_sel:[0,1]
	v_pk_fma_f32 v[204:205], v[132:133], v[204:205], v[240:241]
	v_pk_fma_f32 v[116:117], v[204:205], s[30:31], v[172:173] op_sel_hi:[1,0,1]
	v_pk_add_f32 v[206:207], v[206:207], v[248:249] op_sel_hi:[1,0] neg_lo:[0,1] neg_hi:[0,1]
	v_pk_mul_f32 v[206:207], v[206:207], v[248:249] op_sel:[0,1]
	v_pk_fma_f32 v[206:207], v[134:135], v[206:207], v[242:243]
	v_pk_fma_f32 v[118:119], v[206:207], s[30:31], v[174:175] op_sel_hi:[1,0,1]
	v_pk_add_f32 v[208:209], v[208:209], v[248:249] op_sel_hi:[1,0] neg_lo:[0,1] neg_hi:[0,1]
	v_pk_mul_f32 v[208:209], v[208:209], v[248:249] op_sel:[0,1]
	v_pk_fma_f32 v[208:209], v[136:137], v[208:209], v[244:245]
	v_pk_fma_f32 v[120:121], v[208:209], s[30:31], v[176:177] op_sel_hi:[1,0,1]
	v_pk_add_f32 v[210:211], v[210:211], v[250:251] op_sel_hi:[1,0] neg_lo:[0,1] neg_hi:[0,1]
	v_pk_mul_f32 v[210:211], v[210:211], v[250:251] op_sel:[0,1]
	v_pk_fma_f32 v[210:211], v[130:131], v[210:211], v[238:239]
	v_pk_fma_f32 v[122:123], v[210:211], s[30:31], v[178:179] op_sel_hi:[1,0,1]
	v_pk_add_f32 v[212:213], v[212:213], v[250:251] op_sel_hi:[1,0] neg_lo:[0,1] neg_hi:[0,1]
	v_pk_mul_f32 v[212:213], v[212:213], v[250:251] op_sel:[0,1]
	v_pk_fma_f32 v[212:213], v[132:133], v[212:213], v[240:241]
	v_pk_fma_f32 v[124:125], v[212:213], s[30:31], v[180:181] op_sel_hi:[1,0,1]
	v_pk_add_f32 v[214:215], v[214:215], v[250:251] op_sel_hi:[1,0] neg_lo:[0,1] neg_hi:[0,1]
	v_pk_mul_f32 v[214:215], v[214:215], v[250:251] op_sel:[0,1]
	v_pk_fma_f32 v[214:215], v[134:135], v[214:215], v[242:243]
	v_pk_fma_f32 v[126:127], v[214:215], s[30:31], v[182:183] op_sel_hi:[1,0,1]
	v_pk_add_f32 v[216:217], v[216:217], v[250:251] op_sel_hi:[1,0] neg_lo:[0,1] neg_hi:[0,1]
	v_pk_mul_f32 v[216:217], v[216:217], v[250:251] op_sel:[0,1]
	v_pk_fma_f32 v[216:217], v[136:137], v[216:217], v[244:245]
	v_pk_fma_f32 v[128:129], v[216:217], s[30:31], v[184:185] op_sel_hi:[1,0,1]
	s_mov_b32 s10, 0x200
	v_lshl_add_u64 v[150:151], v[226:227], 0, s[10:11]
	v_lshl_add_u64 v[218:219], v[150:151], 0, s[4:5]
	v_lshl_add_u64 v[220:221], v[218:219], 0, s[4:5]
	v_lshl_add_u64 v[222:223], v[220:221], 0, s[4:5]
	global_load_dwordx2 v[138:139], v149, s[12:13] offset:0
	global_load_dwordx2 v[246:247], v149, s[12:13] offset:256
	global_load_dwordx2 v[248:249], v149, s[12:13] offset:512
	global_load_dwordx2 v[250:251], v149, s[12:13] offset:768
	global_load_dwordx4 v[130:133], v152, s[14:15] offset:512
	global_load_dwordx4 v[134:137], v152, s[14:15] offset:528
	global_load_dwordx4 v[238:241], v152, s[16:17] offset:512
	global_load_dwordx4 v[242:245], v152, s[16:17] offset:528
	global_load_dwordx4 v[186:189], v[150:151], off
	global_load_dwordx4 v[190:193], v[150:151], off offset:16
	global_load_dwordx4 v[194:197], v[218:219], off
	global_load_dwordx4 v[198:201], v[218:219], off offset:16
	global_load_dwordx4 v[202:205], v[220:221], off
	global_load_dwordx4 v[206:209], v[220:221], off offset:16
	global_load_dwordx4 v[210:213], v[222:223], off
	global_load_dwordx4 v[214:217], v[222:223], off offset:16
	ds_write2st64_b32 v153, v66, v67 offset1:2
	ds_write2st64_b32 v153, v68, v69 offset0:4 offset1:6
	ds_write2st64_b32 v252, v70, v71 offset1:2
	ds_write2st64_b32 v252, v72, v73 offset0:4 offset1:6
	ds_write2st64_b32 v153, v74, v75 offset0:32 offset1:34
	ds_write2st64_b32 v153, v76, v77 offset0:36 offset1:38
	ds_write2st64_b32 v252, v78, v79 offset0:32 offset1:34
	ds_write2st64_b32 v252, v80, v81 offset0:36 offset1:38
	ds_write2st64_b32 v153, v82, v83 offset0:64 offset1:66
	ds_write2st64_b32 v153, v84, v85 offset0:68 offset1:70
	ds_write2st64_b32 v252, v86, v87 offset0:64 offset1:66
	ds_write2st64_b32 v252, v88, v89 offset0:68 offset1:70
	ds_write2st64_b32 v153, v90, v91 offset0:96 offset1:98
	ds_write2st64_b32 v153, v92, v93 offset0:100 offset1:102
	ds_write2st64_b32 v252, v94, v95 offset0:96 offset1:98
	ds_write2st64_b32 v252, v96, v97 offset0:100 offset1:102
	s_waitcnt lgkmcnt(0)
	s_barrier
	ds_read_b128 v[154:157], v147
	ds_read_b128 v[158:161], v148
	ds_read_b128 v[162:165], v146
	ds_read_b128 v[166:169], v145
	ds_read_b128 v[170:173], v144
	ds_read_b128 v[174:177], v143
	ds_read_b128 v[178:181], v141
	ds_read_b128 v[182:185], v140
	s_waitcnt vmcnt(0) lgkmcnt(0)
	s_barrier
	v_pk_add_f32 v[186:187], v[186:187], v[138:139] op_sel_hi:[1,0] neg_lo:[0,1] neg_hi:[0,1]
	v_pk_mul_f32 v[186:187], v[186:187], v[138:139] op_sel:[0,1]
	v_pk_fma_f32 v[186:187], v[130:131], v[186:187], v[238:239]
	v_pk_fma_f32 v[66:67], v[186:187], s[30:31], v[154:155] op_sel_hi:[1,0,1]
	v_pk_add_f32 v[188:189], v[188:189], v[138:139] op_sel_hi:[1,0] neg_lo:[0,1] neg_hi:[0,1]
	v_pk_mul_f32 v[188:189], v[188:189], v[138:139] op_sel:[0,1]
	v_pk_fma_f32 v[188:189], v[132:133], v[188:189], v[240:241]
	v_pk_fma_f32 v[68:69], v[188:189], s[30:31], v[156:157] op_sel_hi:[1,0,1]
	v_pk_add_f32 v[190:191], v[190:191], v[138:139] op_sel_hi:[1,0] neg_lo:[0,1] neg_hi:[0,1]
	v_pk_mul_f32 v[190:191], v[190:191], v[138:139] op_sel:[0,1]
	v_pk_fma_f32 v[190:191], v[134:135], v[190:191], v[242:243]
	v_pk_fma_f32 v[70:71], v[190:191], s[30:31], v[158:159] op_sel_hi:[1,0,1]
	v_pk_add_f32 v[192:193], v[192:193], v[138:139] op_sel_hi:[1,0] neg_lo:[0,1] neg_hi:[0,1]
	v_pk_mul_f32 v[192:193], v[192:193], v[138:139] op_sel:[0,1]
	v_pk_fma_f32 v[192:193], v[136:137], v[192:193], v[244:245]
	v_pk_fma_f32 v[72:73], v[192:193], s[30:31], v[160:161] op_sel_hi:[1,0,1]
	v_pk_add_f32 v[194:195], v[194:195], v[246:247] op_sel_hi:[1,0] neg_lo:[0,1] neg_hi:[0,1]
	v_pk_mul_f32 v[194:195], v[194:195], v[246:247] op_sel:[0,1]
	v_pk_fma_f32 v[194:195], v[130:131], v[194:195], v[238:239]
	v_pk_fma_f32 v[74:75], v[194:195], s[30:31], v[162:163] op_sel_hi:[1,0,1]
	v_pk_add_f32 v[196:197], v[196:197], v[246:247] op_sel_hi:[1,0] neg_lo:[0,1] neg_hi:[0,1]
	v_pk_mul_f32 v[196:197], v[196:197], v[246:247] op_sel:[0,1]
	v_pk_fma_f32 v[196:197], v[132:133], v[196:197], v[240:241]
	v_pk_fma_f32 v[76:77], v[196:197], s[30:31], v[164:165] op_sel_hi:[1,0,1]
	v_pk_add_f32 v[198:199], v[198:199], v[246:247] op_sel_hi:[1,0] neg_lo:[0,1] neg_hi:[0,1]
	v_pk_mul_f32 v[198:199], v[198:199], v[246:247] op_sel:[0,1]
	v_pk_fma_f32 v[198:199], v[134:135], v[198:199], v[242:243]
	v_pk_fma_f32 v[78:79], v[198:199], s[30:31], v[166:167] op_sel_hi:[1,0,1]
	v_pk_add_f32 v[200:201], v[200:201], v[246:247] op_sel_hi:[1,0] neg_lo:[0,1] neg_hi:[0,1]
	v_pk_mul_f32 v[200:201], v[200:201], v[246:247] op_sel:[0,1]
	v_pk_fma_f32 v[200:201], v[136:137], v[200:201], v[244:245]
	v_pk_fma_f32 v[80:81], v[200:201], s[30:31], v[168:169] op_sel_hi:[1,0,1]
	v_pk_add_f32 v[202:203], v[202:203], v[248:249] op_sel_hi:[1,0] neg_lo:[0,1] neg_hi:[0,1]
	v_pk_mul_f32 v[202:203], v[202:203], v[248:249] op_sel:[0,1]
	v_pk_fma_f32 v[202:203], v[130:131], v[202:203], v[238:239]
	v_pk_fma_f32 v[82:83], v[202:203], s[30:31], v[170:171] op_sel_hi:[1,0,1]
	v_pk_add_f32 v[204:205], v[204:205], v[248:249] op_sel_hi:[1,0] neg_lo:[0,1] neg_hi:[0,1]
	v_pk_mul_f32 v[204:205], v[204:205], v[248:249] op_sel:[0,1]
	v_pk_fma_f32 v[204:205], v[132:133], v[204:205], v[240:241]
	v_pk_fma_f32 v[84:85], v[204:205], s[30:31], v[172:173] op_sel_hi:[1,0,1]
	v_pk_add_f32 v[206:207], v[206:207], v[248:249] op_sel_hi:[1,0] neg_lo:[0,1] neg_hi:[0,1]
	v_pk_mul_f32 v[206:207], v[206:207], v[248:249] op_sel:[0,1]
	v_pk_fma_f32 v[206:207], v[134:135], v[206:207], v[242:243]
	v_pk_fma_f32 v[86:87], v[206:207], s[30:31], v[174:175] op_sel_hi:[1,0,1]
	v_pk_add_f32 v[208:209], v[208:209], v[248:249] op_sel_hi:[1,0] neg_lo:[0,1] neg_hi:[0,1]
	v_pk_mul_f32 v[208:209], v[208:209], v[248:249] op_sel:[0,1]
	v_pk_fma_f32 v[208:209], v[136:137], v[208:209], v[244:245]
	v_pk_fma_f32 v[88:89], v[208:209], s[30:31], v[176:177] op_sel_hi:[1,0,1]
	v_pk_add_f32 v[210:211], v[210:211], v[250:251] op_sel_hi:[1,0] neg_lo:[0,1] neg_hi:[0,1]
	v_pk_mul_f32 v[210:211], v[210:211], v[250:251] op_sel:[0,1]
	v_pk_fma_f32 v[210:211], v[130:131], v[210:211], v[238:239]
	v_pk_fma_f32 v[90:91], v[210:211], s[30:31], v[178:179] op_sel_hi:[1,0,1]
	v_pk_add_f32 v[212:213], v[212:213], v[250:251] op_sel_hi:[1,0] neg_lo:[0,1] neg_hi:[0,1]
	v_pk_mul_f32 v[212:213], v[212:213], v[250:251] op_sel:[0,1]
	v_pk_fma_f32 v[212:213], v[132:133], v[212:213], v[240:241]
	v_pk_fma_f32 v[92:93], v[212:213], s[30:31], v[180:181] op_sel_hi:[1,0,1]
	v_pk_add_f32 v[214:215], v[214:215], v[250:251] op_sel_hi:[1,0] neg_lo:[0,1] neg_hi:[0,1]
	v_pk_mul_f32 v[214:215], v[214:215], v[250:251] op_sel:[0,1]
	v_pk_fma_f32 v[214:215], v[134:135], v[214:215], v[242:243]
	v_pk_fma_f32 v[94:95], v[214:215], s[30:31], v[182:183] op_sel_hi:[1,0,1]
	v_pk_add_f32 v[216:217], v[216:217], v[250:251] op_sel_hi:[1,0] neg_lo:[0,1] neg_hi:[0,1]
	v_pk_mul_f32 v[216:217], v[216:217], v[250:251] op_sel:[0,1]
	v_pk_fma_f32 v[216:217], v[136:137], v[216:217], v[244:245]
	v_pk_fma_f32 v[96:97], v[216:217], s[30:31], v[184:185] op_sel_hi:[1,0,1]
	v_pk_add_f32 v[154:155], v[98:99], v[100:101]
	v_pk_add_f32 v[156:157], v[106:107], v[108:109]
	v_pk_add_f32 v[158:159], v[114:115], v[116:117]
	v_pk_add_f32 v[160:161], v[122:123], v[124:125]
	v_pk_add_f32 v[154:155], v[154:155], v[102:103]
	v_pk_add_f32 v[156:157], v[156:157], v[110:111]
	v_pk_add_f32 v[158:159], v[158:159], v[118:119]
	v_pk_add_f32 v[160:161], v[160:161], v[126:127]
	v_pk_add_f32 v[154:155], v[154:155], v[104:105]
	v_pk_add_f32 v[156:157], v[156:157], v[112:113]
	v_pk_add_f32 v[158:159], v[158:159], v[120:121]
	v_pk_add_f32 v[160:161], v[160:161], v[128:129]
	v_pk_add_f32 v[154:155], v[154:155], v[66:67]
	v_pk_add_f32 v[156:157], v[156:157], v[74:75]
	v_pk_add_f32 v[158:159], v[158:159], v[82:83]
	v_pk_add_f32 v[160:161], v[160:161], v[90:91]
	v_pk_add_f32 v[154:155], v[154:155], v[68:69]
	v_pk_add_f32 v[156:157], v[156:157], v[76:77]
	v_pk_add_f32 v[158:159], v[158:159], v[84:85]
	v_pk_add_f32 v[160:161], v[160:161], v[92:93]
	v_pk_add_f32 v[154:155], v[154:155], v[70:71]
	v_pk_add_f32 v[156:157], v[156:157], v[78:79]
	v_pk_add_f32 v[158:159], v[158:159], v[86:87]
	v_pk_add_f32 v[160:161], v[160:161], v[94:95]
	v_pk_add_f32 v[154:155], v[154:155], v[72:73]
	v_pk_add_f32 v[156:157], v[156:157], v[80:81]
	v_pk_add_f32 v[158:159], v[158:159], v[88:89]
	v_pk_add_f32 v[160:161], v[160:161], v[96:97]
	v_add_f32_e32 v228, v154, v155
	v_add_f32_e32 v230, v156, v157
	v_add_f32_e32 v232, v158, v159
	v_add_f32_e32 v234, v160, v161
	v_add_f32_dpp v228, v228, v228 quad_perm:[1,0,3,2] row_mask:0xf bank_mask:0xf
	v_add_f32_dpp v230, v230, v230 quad_perm:[1,0,3,2] row_mask:0xf bank_mask:0xf
	v_add_f32_dpp v232, v232, v232 quad_perm:[1,0,3,2] row_mask:0xf bank_mask:0xf
	v_add_f32_dpp v234, v234, v234 quad_perm:[1,0,3,2] row_mask:0xf bank_mask:0xf
	v_add_f32_dpp v228, v228, v228 quad_perm:[2,3,0,1] row_mask:0xf bank_mask:0xf
	v_add_f32_dpp v230, v230, v230 quad_perm:[2,3,0,1] row_mask:0xf bank_mask:0xf
	v_add_f32_dpp v232, v232, v232 quad_perm:[2,3,0,1] row_mask:0xf bank_mask:0xf
	v_add_f32_dpp v234, v234, v234 quad_perm:[2,3,0,1] row_mask:0xf bank_mask:0xf
	v_add_f32_dpp v228, v228, v228 row_half_mirror row_mask:0xf bank_mask:0xf
	v_add_f32_dpp v230, v230, v230 row_half_mirror row_mask:0xf bank_mask:0xf
	v_add_f32_dpp v232, v232, v232 row_half_mirror row_mask:0xf bank_mask:0xf
	v_add_f32_dpp v234, v234, v234 row_half_mirror row_mask:0xf bank_mask:0xf
	v_add_f32_dpp v228, v228, v228 row_mirror row_mask:0xf bank_mask:0xf
	v_add_f32_dpp v230, v230, v230 row_mirror row_mask:0xf bank_mask:0xf
	v_add_f32_dpp v232, v232, v232 row_mirror row_mask:0xf bank_mask:0xf
	v_add_f32_dpp v234, v234, v234 row_mirror row_mask:0xf bank_mask:0xf
	v_mul_f32_e32 v228, 0x3b800000, v228
	v_mul_f32_e32 v230, 0x3b800000, v230
	v_mul_f32_e32 v232, 0x3b800000, v232
	v_mul_f32_e32 v234, 0x3b800000, v234
	v_pk_add_f32 v[170:171], v[98:99], v[228:229] op_sel_hi:[1,0] neg_lo:[0,1] neg_hi:[0,1]
	v_pk_mul_f32 v[162:163], v[170:171], v[170:171]
	v_pk_add_f32 v[172:173], v[106:107], v[230:231] op_sel_hi:[1,0] neg_lo:[0,1] neg_hi:[0,1]
	v_pk_mul_f32 v[164:165], v[172:173], v[172:173]
	v_pk_add_f32 v[170:171], v[114:115], v[232:233] op_sel_hi:[1,0] neg_lo:[0,1] neg_hi:[0,1]
	v_pk_mul_f32 v[166:167], v[170:171], v[170:171]
	v_pk_add_f32 v[172:173], v[122:123], v[234:235] op_sel_hi:[1,0] neg_lo:[0,1] neg_hi:[0,1]
	v_pk_mul_f32 v[168:169], v[172:173], v[172:173]
	v_pk_add_f32 v[170:171], v[100:101], v[228:229] op_sel_hi:[1,0] neg_lo:[0,1] neg_hi:[0,1]
	v_pk_fma_f32 v[162:163], v[170:171], v[170:171], v[162:163]
	v_pk_add_f32 v[172:173], v[108:109], v[230:231] op_sel_hi:[1,0] neg_lo:[0,1] neg_hi:[0,1]
	v_pk_fma_f32 v[164:165], v[172:173], v[172:173], v[164:165]
	v_pk_add_f32 v[170:171], v[116:117], v[232:233] op_sel_hi:[1,0] neg_lo:[0,1] neg_hi:[0,1]
	v_pk_fma_f32 v[166:167], v[170:171], v[170:171], v[166:167]
	v_pk_add_f32 v[172:173], v[124:125], v[234:235] op_sel_hi:[1,0] neg_lo:[0,1] neg_hi:[0,1]
	v_pk_fma_f32 v[168:169], v[172:173], v[172:173], v[168:169]
	v_pk_add_f32 v[170:171], v[102:103], v[228:229] op_sel_hi:[1,0] neg_lo:[0,1] neg_hi:[0,1]
	v_pk_fma_f32 v[162:163], v[170:171], v[170:171], v[162:163]
	v_pk_add_f32 v[172:173], v[110:111], v[230:231] op_sel_hi:[1,0] neg_lo:[0,1] neg_hi:[0,1]
	v_pk_fma_f32 v[164:165], v[172:173], v[172:173], v[164:165]
	v_pk_add_f32 v[170:171], v[118:119], v[232:233] op_sel_hi:[1,0] neg_lo:[0,1] neg_hi:[0,1]
	v_pk_fma_f32 v[166:167], v[170:171], v[170:171], v[166:167]
	v_pk_add_f32 v[172:173], v[126:127], v[234:235] op_sel_hi:[1,0] neg_lo:[0,1] neg_hi:[0,1]
	v_pk_fma_f32 v[168:169], v[172:173], v[172:173], v[168:169]
	v_pk_add_f32 v[170:171], v[104:105], v[228:229] op_sel_hi:[1,0] neg_lo:[0,1] neg_hi:[0,1]
	v_pk_fma_f32 v[162:163], v[170:171], v[170:171], v[162:163]
	v_pk_add_f32 v[172:173], v[112:113], v[230:231] op_sel_hi:[1,0] neg_lo:[0,1] neg_hi:[0,1]
	v_pk_fma_f32 v[164:165], v[172:173], v[172:173], v[164:165]
	v_pk_add_f32 v[170:171], v[120:121], v[232:233] op_sel_hi:[1,0] neg_lo:[0,1] neg_hi:[0,1]
	v_pk_fma_f32 v[166:167], v[170:171], v[170:171], v[166:167]
	v_pk_add_f32 v[172:173], v[128:129], v[234:235] op_sel_hi:[1,0] neg_lo:[0,1] neg_hi:[0,1]
	v_pk_fma_f32 v[168:169], v[172:173], v[172:173], v[168:169]
	v_pk_add_f32 v[170:171], v[66:67], v[228:229] op_sel_hi:[1,0] neg_lo:[0,1] neg_hi:[0,1]
	v_pk_fma_f32 v[162:163], v[170:171], v[170:171], v[162:163]
	v_pk_add_f32 v[172:173], v[74:75], v[230:231] op_sel_hi:[1,0] neg_lo:[0,1] neg_hi:[0,1]
	v_pk_fma_f32 v[164:165], v[172:173], v[172:173], v[164:165]
	v_pk_add_f32 v[170:171], v[82:83], v[232:233] op_sel_hi:[1,0] neg_lo:[0,1] neg_hi:[0,1]
	v_pk_fma_f32 v[166:167], v[170:171], v[170:171], v[166:167]
	v_pk_add_f32 v[172:173], v[90:91], v[234:235] op_sel_hi:[1,0] neg_lo:[0,1] neg_hi:[0,1]
	v_pk_fma_f32 v[168:169], v[172:173], v[172:173], v[168:169]
	v_pk_add_f32 v[170:171], v[68:69], v[228:229] op_sel_hi:[1,0] neg_lo:[0,1] neg_hi:[0,1]
	v_pk_fma_f32 v[162:163], v[170:171], v[170:171], v[162:163]
	v_pk_add_f32 v[172:173], v[76:77], v[230:231] op_sel_hi:[1,0] neg_lo:[0,1] neg_hi:[0,1]
	v_pk_fma_f32 v[164:165], v[172:173], v[172:173], v[164:165]
	v_pk_add_f32 v[170:171], v[84:85], v[232:233] op_sel_hi:[1,0] neg_lo:[0,1] neg_hi:[0,1]
	v_pk_fma_f32 v[166:167], v[170:171], v[170:171], v[166:167]
	v_pk_add_f32 v[172:173], v[92:93], v[234:235] op_sel_hi:[1,0] neg_lo:[0,1] neg_hi:[0,1]
	v_pk_fma_f32 v[168:169], v[172:173], v[172:173], v[168:169]
	v_pk_add_f32 v[170:171], v[70:71], v[228:229] op_sel_hi:[1,0] neg_lo:[0,1] neg_hi:[0,1]
	v_pk_fma_f32 v[162:163], v[170:171], v[170:171], v[162:163]
	v_pk_add_f32 v[172:173], v[78:79], v[230:231] op_sel_hi:[1,0] neg_lo:[0,1] neg_hi:[0,1]
	v_pk_fma_f32 v[164:165], v[172:173], v[172:173], v[164:165]
	v_pk_add_f32 v[170:171], v[86:87], v[232:233] op_sel_hi:[1,0] neg_lo:[0,1] neg_hi:[0,1]
	v_pk_fma_f32 v[166:167], v[170:171], v[170:171], v[166:167]
	v_pk_add_f32 v[172:173], v[94:95], v[234:235] op_sel_hi:[1,0] neg_lo:[0,1] neg_hi:[0,1]
	v_pk_fma_f32 v[168:169], v[172:173], v[172:173], v[168:169]
	v_pk_add_f32 v[170:171], v[72:73], v[228:229] op_sel_hi:[1,0] neg_lo:[0,1] neg_hi:[0,1]
	v_pk_fma_f32 v[162:163], v[170:171], v[170:171], v[162:163]
	v_pk_add_f32 v[172:173], v[80:81], v[230:231] op_sel_hi:[1,0] neg_lo:[0,1] neg_hi:[0,1]
	v_pk_fma_f32 v[164:165], v[172:173], v[172:173], v[164:165]
	v_pk_add_f32 v[170:171], v[88:89], v[232:233] op_sel_hi:[1,0] neg_lo:[0,1] neg_hi:[0,1]
	v_pk_fma_f32 v[166:167], v[170:171], v[170:171], v[166:167]
	v_pk_add_f32 v[172:173], v[96:97], v[234:235] op_sel_hi:[1,0] neg_lo:[0,1] neg_hi:[0,1]
	v_pk_fma_f32 v[168:169], v[172:173], v[172:173], v[168:169]
	v_add_f32_e32 v229, v162, v163
	v_add_f32_e32 v231, v164, v165
	v_add_f32_e32 v233, v166, v167
	v_add_f32_e32 v235, v168, v169
	v_add_f32_dpp v229, v229, v229 quad_perm:[1,0,3,2] row_mask:0xf bank_mask:0xf
	v_add_f32_dpp v231, v231, v231 quad_perm:[1,0,3,2] row_mask:0xf bank_mask:0xf
	v_add_f32_dpp v233, v233, v233 quad_perm:[1,0,3,2] row_mask:0xf bank_mask:0xf
	v_add_f32_dpp v235, v235, v235 quad_perm:[1,0,3,2] row_mask:0xf bank_mask:0xf
	v_add_f32_dpp v229, v229, v229 quad_perm:[2,3,0,1] row_mask:0xf bank_mask:0xf
	v_add_f32_dpp v231, v231, v231 quad_perm:[2,3,0,1] row_mask:0xf bank_mask:0xf
	v_add_f32_dpp v233, v233, v233 quad_perm:[2,3,0,1] row_mask:0xf bank_mask:0xf
	v_add_f32_dpp v235, v235, v235 quad_perm:[2,3,0,1] row_mask:0xf bank_mask:0xf
	v_add_f32_dpp v229, v229, v229 row_half_mirror row_mask:0xf bank_mask:0xf
	v_add_f32_dpp v231, v231, v231 row_half_mirror row_mask:0xf bank_mask:0xf
	v_add_f32_dpp v233, v233, v233 row_half_mirror row_mask:0xf bank_mask:0xf
	v_add_f32_dpp v235, v235, v235 row_half_mirror row_mask:0xf bank_mask:0xf
	v_add_f32_dpp v229, v229, v229 row_mirror row_mask:0xf bank_mask:0xf
	v_add_f32_dpp v231, v231, v231 row_mirror row_mask:0xf bank_mask:0xf
	v_add_f32_dpp v233, v233, v233 row_mirror row_mask:0xf bank_mask:0xf
	v_add_f32_dpp v235, v235, v235 row_mirror row_mask:0xf bank_mask:0xf
	s_mov_b32 exec_lo, 0x10001
	s_mov_b32 exec_hi, 0x10001
	global_store_dwordx2 v1, v[228:229], s[18:19] offset:0 sc1
	global_store_dwordx2 v1, v[230:231], s[18:19] offset:256 sc1
	global_store_dwordx2 v1, v[232:233], s[18:19] offset:512 sc1
	global_store_dwordx2 v1, v[234:235], s[18:19] offset:768 sc1
	s_mov_b64 exec, -1
	s_waitcnt vmcnt(0)
	s_barrier
	v_readfirstlane_b32 s24, v0
	s_nop 3
	s_lshr_b32 s24, s24, 6
	s_cmp_lg_u32 s24, 0
	s_cbranch_scc1 .Lp17_sigA_done
	v_mov_b32_e32 v182, 0
	v_mov_b32_e32 v183, 1
	s_mov_b64 exec, 1
	global_atomic_add v182, v183, s[20:21]
	s_mov_b64 exec, -1
.Lp17_sigA_done:
	s_mov_b32 s10, 0x80000
	v_lshl_add_u64 v[150:151], v[226:227], 0, s[10:11]
	v_lshl_add_u64 v[218:219], v[150:151], 0, s[4:5]
	v_lshl_add_u64 v[220:221], v[218:219], 0, s[4:5]
	v_lshl_add_u64 v[222:223], v[220:221], 0, s[4:5]
	global_load_dwordx2 v[138:139], v149, s[12:13] offset:1024
	global_load_dwordx2 v[246:247], v149, s[12:13] offset:1280
	global_load_dwordx2 v[248:249], v149, s[12:13] offset:1536
	global_load_dwordx2 v[250:251], v149, s[12:13] offset:1792
	global_load_dwordx4 v[130:133], v152, s[14:15] offset:0
	global_load_dwordx4 v[134:137], v152, s[14:15] offset:16
	global_load_dwordx4 v[238:241], v152, s[16:17] offset:0
	global_load_dwordx4 v[242:245], v152, s[16:17] offset:16
	global_load_dwordx4 v[186:189], v[150:151], off
	global_load_dwordx4 v[190:193], v[150:151], off offset:16
	global_load_dwordx4 v[194:197], v[218:219], off
	global_load_dwordx4 v[198:201], v[218:219], off offset:16
	global_load_dwordx4 v[202:205], v[220:221], off
	global_load_dwordx4 v[206:209], v[220:221], off offset:16
	global_load_dwordx4 v[210:213], v[222:223], off
	global_load_dwordx4 v[214:217], v[222:223], off offset:16
	ds_write2st64_b32 v153, v34, v35 offset1:2
	ds_write2st64_b32 v153, v36, v37 offset0:4 offset1:6
	ds_write2st64_b32 v252, v38, v39 offset1:2
	ds_write2st64_b32 v252, v40, v41 offset0:4 offset1:6
	ds_write2st64_b32 v153, v42, v43 offset0:32 offset1:34
	ds_write2st64_b32 v153, v44, v45 offset0:36 offset1:38
	ds_write2st64_b32 v252, v46, v47 offset0:32 offset1:34
	ds_write2st64_b32 v252, v48, v49 offset0:36 offset1:38
	ds_write2st64_b32 v153, v50, v51 offset0:64 offset1:66
	ds_write2st64_b32 v153, v52, v53 offset0:68 offset1:70
	ds_write2st64_b32 v252, v54, v55 offset0:64 offset1:66
	ds_write2st64_b32 v252, v56, v57 offset0:68 offset1:70
	ds_write2st64_b32 v153, v58, v59 offset0:96 offset1:98
	ds_write2st64_b32 v153, v60, v61 offset0:100 offset1:102
	ds_write2st64_b32 v252, v62, v63 offset0:96 offset1:98
	ds_write2st64_b32 v252, v64, v65 offset0:100 offset1:102
	s_waitcnt lgkmcnt(0)
	s_barrier
	ds_read_b128 v[154:157], v147
	ds_read_b128 v[158:161], v148
	ds_read_b128 v[162:165], v146
	ds_read_b128 v[166:169], v145
	ds_read_b128 v[170:173], v144
	ds_read_b128 v[174:177], v143
	ds_read_b128 v[178:181], v141
	ds_read_b128 v[182:185], v140
	s_waitcnt vmcnt(0) lgkmcnt(0)
	s_barrier
	v_pk_add_f32 v[186:187], v[186:187], v[138:139] op_sel_hi:[1,0] neg_lo:[0,1] neg_hi:[0,1]
	v_pk_mul_f32 v[186:187], v[186:187], v[138:139] op_sel:[0,1]
	v_pk_fma_f32 v[186:187], v[130:131], v[186:187], v[238:239]
	v_pk_fma_f32 v[34:35], v[186:187], s[30:31], v[154:155] op_sel_hi:[1,0,1]
	v_pk_add_f32 v[188:189], v[188:189], v[138:139] op_sel_hi:[1,0] neg_lo:[0,1] neg_hi:[0,1]
	v_pk_mul_f32 v[188:189], v[188:189], v[138:139] op_sel:[0,1]
	v_pk_fma_f32 v[188:189], v[132:133], v[188:189], v[240:241]
	v_pk_fma_f32 v[36:37], v[188:189], s[30:31], v[156:157] op_sel_hi:[1,0,1]
	v_pk_add_f32 v[190:191], v[190:191], v[138:139] op_sel_hi:[1,0] neg_lo:[0,1] neg_hi:[0,1]
	v_pk_mul_f32 v[190:191], v[190:191], v[138:139] op_sel:[0,1]
	v_pk_fma_f32 v[190:191], v[134:135], v[190:191], v[242:243]
	v_pk_fma_f32 v[38:39], v[190:191], s[30:31], v[158:159] op_sel_hi:[1,0,1]
	v_pk_add_f32 v[192:193], v[192:193], v[138:139] op_sel_hi:[1,0] neg_lo:[0,1] neg_hi:[0,1]
	v_pk_mul_f32 v[192:193], v[192:193], v[138:139] op_sel:[0,1]
	v_pk_fma_f32 v[192:193], v[136:137], v[192:193], v[244:245]
	v_pk_fma_f32 v[40:41], v[192:193], s[30:31], v[160:161] op_sel_hi:[1,0,1]
	v_pk_add_f32 v[194:195], v[194:195], v[246:247] op_sel_hi:[1,0] neg_lo:[0,1] neg_hi:[0,1]
	v_pk_mul_f32 v[194:195], v[194:195], v[246:247] op_sel:[0,1]
	v_pk_fma_f32 v[194:195], v[130:131], v[194:195], v[238:239]
	v_pk_fma_f32 v[42:43], v[194:195], s[30:31], v[162:163] op_sel_hi:[1,0,1]
	v_pk_add_f32 v[196:197], v[196:197], v[246:247] op_sel_hi:[1,0] neg_lo:[0,1] neg_hi:[0,1]
	v_pk_mul_f32 v[196:197], v[196:197], v[246:247] op_sel:[0,1]
	v_pk_fma_f32 v[196:197], v[132:133], v[196:197], v[240:241]
	v_pk_fma_f32 v[44:45], v[196:197], s[30:31], v[164:165] op_sel_hi:[1,0,1]
	v_pk_add_f32 v[198:199], v[198:199], v[246:247] op_sel_hi:[1,0] neg_lo:[0,1] neg_hi:[0,1]
	v_pk_mul_f32 v[198:199], v[198:199], v[246:247] op_sel:[0,1]
	v_pk_fma_f32 v[198:199], v[134:135], v[198:199], v[242:243]
	v_pk_fma_f32 v[46:47], v[198:199], s[30:31], v[166:167] op_sel_hi:[1,0,1]
	v_pk_add_f32 v[200:201], v[200:201], v[246:247] op_sel_hi:[1,0] neg_lo:[0,1] neg_hi:[0,1]
	v_pk_mul_f32 v[200:201], v[200:201], v[246:247] op_sel:[0,1]
	v_pk_fma_f32 v[200:201], v[136:137], v[200:201], v[244:245]
	v_pk_fma_f32 v[48:49], v[200:201], s[30:31], v[168:169] op_sel_hi:[1,0,1]
	v_pk_add_f32 v[202:203], v[202:203], v[248:249] op_sel_hi:[1,0] neg_lo:[0,1] neg_hi:[0,1]
	v_pk_mul_f32 v[202:203], v[202:203], v[248:249] op_sel:[0,1]
	v_pk_fma_f32 v[202:203], v[130:131], v[202:203], v[238:239]
	v_pk_fma_f32 v[50:51], v[202:203], s[30:31], v[170:171] op_sel_hi:[1,0,1]
	v_pk_add_f32 v[204:205], v[204:205], v[248:249] op_sel_hi:[1,0] neg_lo:[0,1] neg_hi:[0,1]
	v_pk_mul_f32 v[204:205], v[204:205], v[248:249] op_sel:[0,1]
	v_pk_fma_f32 v[204:205], v[132:133], v[204:205], v[240:241]
	v_pk_fma_f32 v[52:53], v[204:205], s[30:31], v[172:173] op_sel_hi:[1,0,1]
	v_pk_add_f32 v[206:207], v[206:207], v[248:249] op_sel_hi:[1,0] neg_lo:[0,1] neg_hi:[0,1]
	v_pk_mul_f32 v[206:207], v[206:207], v[248:249] op_sel:[0,1]
	v_pk_fma_f32 v[206:207], v[134:135], v[206:207], v[242:243]
	v_pk_fma_f32 v[54:55], v[206:207], s[30:31], v[174:175] op_sel_hi:[1,0,1]
	v_pk_add_f32 v[208:209], v[208:209], v[248:249] op_sel_hi:[1,0] neg_lo:[0,1] neg_hi:[0,1]
	v_pk_mul_f32 v[208:209], v[208:209], v[248:249] op_sel:[0,1]
	v_pk_fma_f32 v[208:209], v[136:137], v[208:209], v[244:245]
	v_pk_fma_f32 v[56:57], v[208:209], s[30:31], v[176:177] op_sel_hi:[1,0,1]
	v_pk_add_f32 v[210:211], v[210:211], v[250:251] op_sel_hi:[1,0] neg_lo:[0,1] neg_hi:[0,1]
	v_pk_mul_f32 v[210:211], v[210:211], v[250:251] op_sel:[0,1]
	v_pk_fma_f32 v[210:211], v[130:131], v[210:211], v[238:239]
	v_pk_fma_f32 v[58:59], v[210:211], s[30:31], v[178:179] op_sel_hi:[1,0,1]
	v_pk_add_f32 v[212:213], v[212:213], v[250:251] op_sel_hi:[1,0] neg_lo:[0,1] neg_hi:[0,1]
	v_pk_mul_f32 v[212:213], v[212:213], v[250:251] op_sel:[0,1]
	v_pk_fma_f32 v[212:213], v[132:133], v[212:213], v[240:241]
	v_pk_fma_f32 v[60:61], v[212:213], s[30:31], v[180:181] op_sel_hi:[1,0,1]
	v_pk_add_f32 v[214:215], v[214:215], v[250:251] op_sel_hi:[1,0] neg_lo:[0,1] neg_hi:[0,1]
	v_pk_mul_f32 v[214:215], v[214:215], v[250:251] op_sel:[0,1]
	v_pk_fma_f32 v[214:215], v[134:135], v[214:215], v[242:243]
	v_pk_fma_f32 v[62:63], v[214:215], s[30:31], v[182:183] op_sel_hi:[1,0,1]
	v_pk_add_f32 v[216:217], v[216:217], v[250:251] op_sel_hi:[1,0] neg_lo:[0,1] neg_hi:[0,1]
	v_pk_mul_f32 v[216:217], v[216:217], v[250:251] op_sel:[0,1]
	v_pk_fma_f32 v[216:217], v[136:137], v[216:217], v[244:245]
	v_pk_fma_f32 v[64:65], v[216:217], s[30:31], v[184:185] op_sel_hi:[1,0,1]
	s_mov_b32 s10, 0x80200
	v_lshl_add_u64 v[150:151], v[226:227], 0, s[10:11]
	v_lshl_add_u64 v[218:219], v[150:151], 0, s[4:5]
	v_lshl_add_u64 v[220:221], v[218:219], 0, s[4:5]
	v_lshl_add_u64 v[222:223], v[220:221], 0, s[4:5]
	global_load_dwordx2 v[138:139], v149, s[12:13] offset:1024
	global_load_dwordx2 v[246:247], v149, s[12:13] offset:1280
	global_load_dwordx2 v[248:249], v149, s[12:13] offset:1536
	global_load_dwordx2 v[250:251], v149, s[12:13] offset:1792
	global_load_dwordx4 v[130:133], v152, s[14:15] offset:512
	global_load_dwordx4 v[134:137], v152, s[14:15] offset:528
	global_load_dwordx4 v[238:241], v152, s[16:17] offset:512
	global_load_dwordx4 v[242:245], v152, s[16:17] offset:528
	global_load_dwordx4 v[186:189], v[150:151], off
	global_load_dwordx4 v[190:193], v[150:151], off offset:16
	global_load_dwordx4 v[194:197], v[218:219], off
	global_load_dwordx4 v[198:201], v[218:219], off offset:16
	global_load_dwordx4 v[202:205], v[220:221], off
	global_load_dwordx4 v[206:209], v[220:221], off offset:16
	global_load_dwordx4 v[210:213], v[222:223], off
	global_load_dwordx4 v[214:217], v[222:223], off offset:16
	ds_write2st64_b32 v153, v2, v3 offset1:2
	ds_write2st64_b32 v153, v4, v5 offset0:4 offset1:6
	ds_write2st64_b32 v252, v6, v7 offset1:2
	ds_write2st64_b32 v252, v8, v9 offset0:4 offset1:6
	ds_write2st64_b32 v153, v10, v11 offset0:32 offset1:34
	ds_write2st64_b32 v153, v12, v13 offset0:36 offset1:38
	ds_write2st64_b32 v252, v14, v15 offset0:32 offset1:34
	ds_write2st64_b32 v252, v16, v17 offset0:36 offset1:38
	ds_write2st64_b32 v153, v18, v19 offset0:64 offset1:66
	ds_write2st64_b32 v153, v20, v21 offset0:68 offset1:70
	ds_write2st64_b32 v252, v22, v23 offset0:64 offset1:66
	ds_write2st64_b32 v252, v24, v25 offset0:68 offset1:70
	ds_write2st64_b32 v153, v26, v27 offset0:96 offset1:98
	ds_write2st64_b32 v153, v28, v29 offset0:100 offset1:102
	ds_write2st64_b32 v252, v30, v31 offset0:96 offset1:98
	ds_write2st64_b32 v252, v32, v33 offset0:100 offset1:102
	s_waitcnt lgkmcnt(0)
	s_barrier
	ds_read_b128 v[154:157], v147
	ds_read_b128 v[158:161], v148
	ds_read_b128 v[162:165], v146
	ds_read_b128 v[166:169], v145
	ds_read_b128 v[170:173], v144
	ds_read_b128 v[174:177], v143
	ds_read_b128 v[178:181], v141
	ds_read_b128 v[182:185], v140
	s_waitcnt vmcnt(0) lgkmcnt(0)
	s_barrier
	v_pk_add_f32 v[186:187], v[186:187], v[138:139] op_sel_hi:[1,0] neg_lo:[0,1] neg_hi:[0,1]
	v_pk_mul_f32 v[186:187], v[186:187], v[138:139] op_sel:[0,1]
	v_pk_fma_f32 v[186:187], v[130:131], v[186:187], v[238:239]
	v_pk_fma_f32 v[2:3], v[186:187], s[30:31], v[154:155] op_sel_hi:[1,0,1]
	v_pk_add_f32 v[188:189], v[188:189], v[138:139] op_sel_hi:[1,0] neg_lo:[0,1] neg_hi:[0,1]
	v_pk_mul_f32 v[188:189], v[188:189], v[138:139] op_sel:[0,1]
	v_pk_fma_f32 v[188:189], v[132:133], v[188:189], v[240:241]
	v_pk_fma_f32 v[4:5], v[188:189], s[30:31], v[156:157] op_sel_hi:[1,0,1]
	v_pk_add_f32 v[190:191], v[190:191], v[138:139] op_sel_hi:[1,0] neg_lo:[0,1] neg_hi:[0,1]
	v_pk_mul_f32 v[190:191], v[190:191], v[138:139] op_sel:[0,1]
	v_pk_fma_f32 v[190:191], v[134:135], v[190:191], v[242:243]
	v_pk_fma_f32 v[6:7], v[190:191], s[30:31], v[158:159] op_sel_hi:[1,0,1]
	v_pk_add_f32 v[192:193], v[192:193], v[138:139] op_sel_hi:[1,0] neg_lo:[0,1] neg_hi:[0,1]
	v_pk_mul_f32 v[192:193], v[192:193], v[138:139] op_sel:[0,1]
	v_pk_fma_f32 v[192:193], v[136:137], v[192:193], v[244:245]
	v_pk_fma_f32 v[8:9], v[192:193], s[30:31], v[160:161] op_sel_hi:[1,0,1]
	v_pk_add_f32 v[194:195], v[194:195], v[246:247] op_sel_hi:[1,0] neg_lo:[0,1] neg_hi:[0,1]
	v_pk_mul_f32 v[194:195], v[194:195], v[246:247] op_sel:[0,1]
	v_pk_fma_f32 v[194:195], v[130:131], v[194:195], v[238:239]
	v_pk_fma_f32 v[10:11], v[194:195], s[30:31], v[162:163] op_sel_hi:[1,0,1]
	v_pk_add_f32 v[196:197], v[196:197], v[246:247] op_sel_hi:[1,0] neg_lo:[0,1] neg_hi:[0,1]
	v_pk_mul_f32 v[196:197], v[196:197], v[246:247] op_sel:[0,1]
	v_pk_fma_f32 v[196:197], v[132:133], v[196:197], v[240:241]
	v_pk_fma_f32 v[12:13], v[196:197], s[30:31], v[164:165] op_sel_hi:[1,0,1]
	v_pk_add_f32 v[198:199], v[198:199], v[246:247] op_sel_hi:[1,0] neg_lo:[0,1] neg_hi:[0,1]
	v_pk_mul_f32 v[198:199], v[198:199], v[246:247] op_sel:[0,1]
	v_pk_fma_f32 v[198:199], v[134:135], v[198:199], v[242:243]
	v_pk_fma_f32 v[14:15], v[198:199], s[30:31], v[166:167] op_sel_hi:[1,0,1]
	v_pk_add_f32 v[200:201], v[200:201], v[246:247] op_sel_hi:[1,0] neg_lo:[0,1] neg_hi:[0,1]
	v_pk_mul_f32 v[200:201], v[200:201], v[246:247] op_sel:[0,1]
	v_pk_fma_f32 v[200:201], v[136:137], v[200:201], v[244:245]
	v_pk_fma_f32 v[16:17], v[200:201], s[30:31], v[168:169] op_sel_hi:[1,0,1]
	v_pk_add_f32 v[202:203], v[202:203], v[248:249] op_sel_hi:[1,0] neg_lo:[0,1] neg_hi:[0,1]
	v_pk_mul_f32 v[202:203], v[202:203], v[248:249] op_sel:[0,1]
	v_pk_fma_f32 v[202:203], v[130:131], v[202:203], v[238:239]
	v_pk_fma_f32 v[18:19], v[202:203], s[30:31], v[170:171] op_sel_hi:[1,0,1]
	v_pk_add_f32 v[204:205], v[204:205], v[248:249] op_sel_hi:[1,0] neg_lo:[0,1] neg_hi:[0,1]
	v_pk_mul_f32 v[204:205], v[204:205], v[248:249] op_sel:[0,1]
	v_pk_fma_f32 v[204:205], v[132:133], v[204:205], v[240:241]
	v_pk_fma_f32 v[20:21], v[204:205], s[30:31], v[172:173] op_sel_hi:[1,0,1]
	v_pk_add_f32 v[206:207], v[206:207], v[248:249] op_sel_hi:[1,0] neg_lo:[0,1] neg_hi:[0,1]
	v_pk_mul_f32 v[206:207], v[206:207], v[248:249] op_sel:[0,1]
	v_pk_fma_f32 v[206:207], v[134:135], v[206:207], v[242:243]
	v_pk_fma_f32 v[22:23], v[206:207], s[30:31], v[174:175] op_sel_hi:[1,0,1]
	v_pk_add_f32 v[208:209], v[208:209], v[248:249] op_sel_hi:[1,0] neg_lo:[0,1] neg_hi:[0,1]
	v_pk_mul_f32 v[208:209], v[208:209], v[248:249] op_sel:[0,1]
	v_pk_fma_f32 v[208:209], v[136:137], v[208:209], v[244:245]
	v_pk_fma_f32 v[24:25], v[208:209], s[30:31], v[176:177] op_sel_hi:[1,0,1]
	v_pk_add_f32 v[210:211], v[210:211], v[250:251] op_sel_hi:[1,0] neg_lo:[0,1] neg_hi:[0,1]
	v_pk_mul_f32 v[210:211], v[210:211], v[250:251] op_sel:[0,1]
	v_pk_fma_f32 v[210:211], v[130:131], v[210:211], v[238:239]
	v_pk_fma_f32 v[26:27], v[210:211], s[30:31], v[178:179] op_sel_hi:[1,0,1]
	v_pk_add_f32 v[212:213], v[212:213], v[250:251] op_sel_hi:[1,0] neg_lo:[0,1] neg_hi:[0,1]
	v_pk_mul_f32 v[212:213], v[212:213], v[250:251] op_sel:[0,1]
	v_pk_fma_f32 v[212:213], v[132:133], v[212:213], v[240:241]
	v_pk_fma_f32 v[28:29], v[212:213], s[30:31], v[180:181] op_sel_hi:[1,0,1]
	v_pk_add_f32 v[214:215], v[214:215], v[250:251] op_sel_hi:[1,0] neg_lo:[0,1] neg_hi:[0,1]
	v_pk_mul_f32 v[214:215], v[214:215], v[250:251] op_sel:[0,1]
	v_pk_fma_f32 v[214:215], v[134:135], v[214:215], v[242:243]
	v_pk_fma_f32 v[30:31], v[214:215], s[30:31], v[182:183] op_sel_hi:[1,0,1]
	v_pk_add_f32 v[216:217], v[216:217], v[250:251] op_sel_hi:[1,0] neg_lo:[0,1] neg_hi:[0,1]
	v_pk_mul_f32 v[216:217], v[216:217], v[250:251] op_sel:[0,1]
	v_pk_fma_f32 v[216:217], v[136:137], v[216:217], v[244:245]
	v_pk_fma_f32 v[32:33], v[216:217], s[30:31], v[184:185] op_sel_hi:[1,0,1]
	v_readfirstlane_b32 s24, v0
	s_nop 3
	s_lshr_b32 s24, s24, 6
	s_cmp_lg_u32 s24, 0
	s_cbranch_scc1 .Lp17_pollA_done
	v_mov_b32_e32 v182, 0
	s_mov_b64 exec, 1
	s_mov_b32 s25, 0
.Lp17_pollA:
	global_load_dword v184, v182, s[20:21] sc1
	s_waitcnt vmcnt(0)
	v_readfirstlane_b32 s24, v184
	s_nop 3
	s_cmp_ge_u32 s24, 4
	s_cbranch_scc1 .Lp17_polledA
	s_sleep 1
	s_add_i32 s25, s25, 1
	s_cmp_lt_u32 s25, 0x4000
	s_cbranch_scc1 .Lp17_pollA

.Lp17_pollA_done:
	s_barrier
	v_and_b32_e32 v174, 3, v0
	v_lshl_add_u32 v174, v174, 8, v149
	v_add_u32_e32 v175, 0x1000, v174
	global_load_dwordx2 v[238:239], v174, s[18:19] sc1
	global_load_dwordx2 v[240:241], v174, s[18:19] offset:2048 sc1
	global_load_dwordx2 v[242:243], v175, s[18:19] sc1
	global_load_dwordx2 v[244:245], v175, s[18:19] offset:2048 sc1
	global_load_dwordx4 v[186:189], v152, s[56:57] offset:0
	global_load_dwordx4 v[190:193], v152, s[56:57] offset:16
	global_load_dwordx4 v[194:197], v152, s[56:57] offset:512
	global_load_dwordx4 v[198:201], v152, s[56:57] offset:528
	global_load_dwordx4 v[202:205], v152, s[58:59] offset:0
	global_load_dwordx4 v[206:209], v152, s[58:59] offset:16
	global_load_dwordx4 v[210:213], v152, s[58:59] offset:512
	global_load_dwordx4 v[214:217], v152, s[58:59] offset:528
	v_lshl_add_u64 v[220:221], s[60:61], 0, v[224:225]
	v_pk_add_f32 v[154:155], v[34:35], v[36:37]
	v_pk_add_f32 v[156:157], v[42:43], v[44:45]
	v_pk_add_f32 v[158:159], v[50:51], v[52:53]
	v_pk_add_f32 v[160:161], v[58:59], v[60:61]
	v_pk_add_f32 v[154:155], v[154:155], v[38:39]
	v_pk_add_f32 v[156:157], v[156:157], v[46:47]
	v_pk_add_f32 v[158:159], v[158:159], v[54:55]
	v_pk_add_f32 v[160:161], v[160:161], v[62:63]
	v_pk_add_f32 v[154:155], v[154:155], v[40:41]
	v_pk_add_f32 v[156:157], v[156:157], v[48:49]
	v_pk_add_f32 v[158:159], v[158:159], v[56:57]
	v_pk_add_f32 v[160:161], v[160:161], v[64:65]
	v_pk_add_f32 v[154:155], v[154:155], v[2:3]
	v_pk_add_f32 v[156:157], v[156:157], v[10:11]
	v_pk_add_f32 v[158:159], v[158:159], v[18:19]
	v_pk_add_f32 v[160:161], v[160:161], v[26:27]
	v_pk_add_f32 v[154:155], v[154:155], v[4:5]
	v_pk_add_f32 v[156:157], v[156:157], v[12:13]
	v_pk_add_f32 v[158:159], v[158:159], v[20:21]
	v_pk_add_f32 v[160:161], v[160:161], v[28:29]
	v_pk_add_f32 v[154:155], v[154:155], v[6:7]
	v_pk_add_f32 v[156:157], v[156:157], v[14:15]
	v_pk_add_f32 v[158:159], v[158:159], v[22:23]
	v_pk_add_f32 v[160:161], v[160:161], v[30:31]
	v_pk_add_f32 v[154:155], v[154:155], v[8:9]
	v_pk_add_f32 v[156:157], v[156:157], v[16:17]
	v_pk_add_f32 v[158:159], v[158:159], v[24:25]
	v_pk_add_f32 v[160:161], v[160:161], v[32:33]
	v_add_f32_e32 v130, v154, v155
	v_add_f32_e32 v132, v156, v157
	v_add_f32_e32 v134, v158, v159
	v_add_f32_e32 v136, v160, v161
	v_add_f32_dpp v130, v130, v130 quad_perm:[1,0,3,2] row_mask:0xf bank_mask:0xf
	v_add_f32_dpp v132, v132, v132 quad_perm:[1,0,3,2] row_mask:0xf bank_mask:0xf
	v_add_f32_dpp v134, v134, v134 quad_perm:[1,0,3,2] row_mask:0xf bank_mask:0xf
	v_add_f32_dpp v136, v136, v136 quad_perm:[1,0,3,2] row_mask:0xf bank_mask:0xf
	v_add_f32_dpp v130, v130, v130 quad_perm:[2,3,0,1] row_mask:0xf bank_mask:0xf
	v_add_f32_dpp v132, v132, v132 quad_perm:[2,3,0,1] row_mask:0xf bank_mask:0xf
	v_add_f32_dpp v134, v134, v134 quad_perm:[2,3,0,1] row_mask:0xf bank_mask:0xf
	v_add_f32_dpp v136, v136, v136 quad_perm:[2,3,0,1] row_mask:0xf bank_mask:0xf
	v_add_f32_dpp v130, v130, v130 row_half_mirror row_mask:0xf bank_mask:0xf
	v_add_f32_dpp v132, v132, v132 row_half_mirror row_mask:0xf bank_mask:0xf
	v_add_f32_dpp v134, v134, v134 row_half_mirror row_mask:0xf bank_mask:0xf
	v_add_f32_dpp v136, v136, v136 row_half_mirror row_mask:0xf bank_mask:0xf
	v_add_f32_dpp v130, v130, v130 row_mirror row_mask:0xf bank_mask:0xf
	v_add_f32_dpp v132, v132, v132 row_mirror row_mask:0xf bank_mask:0xf
	v_add_f32_dpp v134, v134, v134 row_mirror row_mask:0xf bank_mask:0xf
	v_add_f32_dpp v136, v136, v136 row_mirror row_mask:0xf bank_mask:0xf
	v_mul_f32_e32 v130, 0x3b800000, v130
	v_mul_f32_e32 v132, 0x3b800000, v132
	v_mul_f32_e32 v134, 0x3b800000, v134
	v_mul_f32_e32 v136, 0x3b800000, v136
	v_pk_add_f32 v[170:171], v[34:35], v[130:131] op_sel_hi:[1,0] neg_lo:[0,1] neg_hi:[0,1]
	v_pk_mul_f32 v[162:163], v[170:171], v[170:171]
	v_pk_add_f32 v[172:173], v[42:43], v[132:133] op_sel_hi:[1,0] neg_lo:[0,1] neg_hi:[0,1]
	v_pk_mul_f32 v[164:165], v[172:173], v[172:173]
	v_pk_add_f32 v[170:171], v[50:51], v[134:135] op_sel_hi:[1,0] neg_lo:[0,1] neg_hi:[0,1]
	v_pk_mul_f32 v[166:167], v[170:171], v[170:171]
	v_pk_add_f32 v[172:173], v[58:59], v[136:137] op_sel_hi:[1,0] neg_lo:[0,1] neg_hi:[0,1]
	v_pk_mul_f32 v[168:169], v[172:173], v[172:173]
	v_pk_add_f32 v[170:171], v[36:37], v[130:131] op_sel_hi:[1,0] neg_lo:[0,1] neg_hi:[0,1]
	v_pk_fma_f32 v[162:163], v[170:171], v[170:171], v[162:163]
	v_pk_add_f32 v[172:173], v[44:45], v[132:133] op_sel_hi:[1,0] neg_lo:[0,1] neg_hi:[0,1]
	v_pk_fma_f32 v[164:165], v[172:173], v[172:173], v[164:165]
	v_pk_add_f32 v[170:171], v[52:53], v[134:135] op_sel_hi:[1,0] neg_lo:[0,1] neg_hi:[0,1]
	v_pk_fma_f32 v[166:167], v[170:171], v[170:171], v[166:167]
	v_pk_add_f32 v[172:173], v[60:61], v[136:137] op_sel_hi:[1,0] neg_lo:[0,1] neg_hi:[0,1]
	v_pk_fma_f32 v[168:169], v[172:173], v[172:173], v[168:169]
	v_pk_add_f32 v[170:171], v[38:39], v[130:131] op_sel_hi:[1,0] neg_lo:[0,1] neg_hi:[0,1]
	v_pk_fma_f32 v[162:163], v[170:171], v[170:171], v[162:163]
	v_pk_add_f32 v[172:173], v[46:47], v[132:133] op_sel_hi:[1,0] neg_lo:[0,1] neg_hi:[0,1]
	v_pk_fma_f32 v[164:165], v[172:173], v[172:173], v[164:165]
	v_pk_add_f32 v[170:171], v[54:55], v[134:135] op_sel_hi:[1,0] neg_lo:[0,1] neg_hi:[0,1]
	v_pk_fma_f32 v[166:167], v[170:171], v[170:171], v[166:167]
	v_pk_add_f32 v[172:173], v[62:63], v[136:137] op_sel_hi:[1,0] neg_lo:[0,1] neg_hi:[0,1]
	v_pk_fma_f32 v[168:169], v[172:173], v[172:173], v[168:169]
	v_pk_add_f32 v[170:171], v[40:41], v[130:131] op_sel_hi:[1,0] neg_lo:[0,1] neg_hi:[0,1]
	v_pk_fma_f32 v[162:163], v[170:171], v[170:171], v[162:163]
	v_pk_add_f32 v[172:173], v[48:49], v[132:133] op_sel_hi:[1,0] neg_lo:[0,1] neg_hi:[0,1]
	v_pk_fma_f32 v[164:165], v[172:173], v[172:173], v[164:165]
	v_pk_add_f32 v[170:171], v[56:57], v[134:135] op_sel_hi:[1,0] neg_lo:[0,1] neg_hi:[0,1]
	v_pk_fma_f32 v[166:167], v[170:171], v[170:171], v[166:167]
	v_pk_add_f32 v[172:173], v[64:65], v[136:137] op_sel_hi:[1,0] neg_lo:[0,1] neg_hi:[0,1]
	v_pk_fma_f32 v[168:169], v[172:173], v[172:173], v[168:169]
	v_pk_add_f32 v[170:171], v[2:3], v[130:131] op_sel_hi:[1,0] neg_lo:[0,1] neg_hi:[0,1]
	v_pk_fma_f32 v[162:163], v[170:171], v[170:171], v[162:163]
	v_pk_add_f32 v[172:173], v[10:11], v[132:133] op_sel_hi:[1,0] neg_lo:[0,1] neg_hi:[0,1]
	v_pk_fma_f32 v[164:165], v[172:173], v[172:173], v[164:165]
	v_pk_add_f32 v[170:171], v[18:19], v[134:135] op_sel_hi:[1,0] neg_lo:[0,1] neg_hi:[0,1]
	v_pk_fma_f32 v[166:167], v[170:171], v[170:171], v[166:167]
	v_pk_add_f32 v[172:173], v[26:27], v[136:137] op_sel_hi:[1,0] neg_lo:[0,1] neg_hi:[0,1]
	v_pk_fma_f32 v[168:169], v[172:173], v[172:173], v[168:169]
	v_pk_add_f32 v[170:171], v[4:5], v[130:131] op_sel_hi:[1,0] neg_lo:[0,1] neg_hi:[0,1]
	v_pk_fma_f32 v[162:163], v[170:171], v[170:171], v[162:163]
	v_pk_add_f32 v[172:173], v[12:13], v[132:133] op_sel_hi:[1,0] neg_lo:[0,1] neg_hi:[0,1]
	v_pk_fma_f32 v[164:165], v[172:173], v[172:173], v[164:165]
	v_pk_add_f32 v[170:171], v[20:21], v[134:135] op_sel_hi:[1,0] neg_lo:[0,1] neg_hi:[0,1]
	v_pk_fma_f32 v[166:167], v[170:171], v[170:171], v[166:167]
	v_pk_add_f32 v[172:173], v[28:29], v[136:137] op_sel_hi:[1,0] neg_lo:[0,1] neg_hi:[0,1]
	v_pk_fma_f32 v[168:169], v[172:173], v[172:173], v[168:169]
	v_pk_add_f32 v[170:171], v[6:7], v[130:131] op_sel_hi:[1,0] neg_lo:[0,1] neg_hi:[0,1]
	v_pk_fma_f32 v[162:163], v[170:171], v[170:171], v[162:163]
	v_pk_add_f32 v[172:173], v[14:15], v[132:133] op_sel_hi:[1,0] neg_lo:[0,1] neg_hi:[0,1]
	v_pk_fma_f32 v[164:165], v[172:173], v[172:173], v[164:165]
	v_pk_add_f32 v[170:171], v[22:23], v[134:135] op_sel_hi:[1,0] neg_lo:[0,1] neg_hi:[0,1]
	v_pk_fma_f32 v[166:167], v[170:171], v[170:171], v[166:167]
	v_pk_add_f32 v[172:173], v[30:31], v[136:137] op_sel_hi:[1,0] neg_lo:[0,1] neg_hi:[0,1]
	v_pk_fma_f32 v[168:169], v[172:173], v[172:173], v[168:169]
	v_pk_add_f32 v[170:171], v[8:9], v[130:131] op_sel_hi:[1,0] neg_lo:[0,1] neg_hi:[0,1]
	v_pk_fma_f32 v[162:163], v[170:171], v[170:171], v[162:163]
	v_pk_add_f32 v[172:173], v[16:17], v[132:133] op_sel_hi:[1,0] neg_lo:[0,1] neg_hi:[0,1]
	v_pk_fma_f32 v[164:165], v[172:173], v[172:173], v[164:165]
	v_pk_add_f32 v[170:171], v[24:25], v[134:135] op_sel_hi:[1,0] neg_lo:[0,1] neg_hi:[0,1]
	v_pk_fma_f32 v[166:167], v[170:171], v[170:171], v[166:167]
	v_pk_add_f32 v[172:173], v[32:33], v[136:137] op_sel_hi:[1,0] neg_lo:[0,1] neg_hi:[0,1]
	v_pk_fma_f32 v[168:169], v[172:173], v[172:173], v[168:169]
	v_add_f32_e32 v131, v162, v163
	v_add_f32_e32 v133, v164, v165
	v_add_f32_e32 v135, v166, v167
	v_add_f32_e32 v137, v168, v169
	v_add_f32_dpp v131, v131, v131 quad_perm:[1,0,3,2] row_mask:0xf bank_mask:0xf
	v_add_f32_dpp v133, v133, v133 quad_perm:[1,0,3,2] row_mask:0xf bank_mask:0xf
	v_add_f32_dpp v135, v135, v135 quad_perm:[1,0,3,2] row_mask:0xf bank_mask:0xf
	v_add_f32_dpp v137, v137, v137 quad_perm:[1,0,3,2] row_mask:0xf bank_mask:0xf
	v_add_f32_dpp v131, v131, v131 quad_perm:[2,3,0,1] row_mask:0xf bank_mask:0xf
	v_add_f32_dpp v133, v133, v133 quad_perm:[2,3,0,1] row_mask:0xf bank_mask:0xf
	v_add_f32_dpp v135, v135, v135 quad_perm:[2,3,0,1] row_mask:0xf bank_mask:0xf
	v_add_f32_dpp v137, v137, v137 quad_perm:[2,3,0,1] row_mask:0xf bank_mask:0xf
	v_add_f32_dpp v131, v131, v131 row_half_mirror row_mask:0xf bank_mask:0xf
	v_add_f32_dpp v133, v133, v133 row_half_mirror row_mask:0xf bank_mask:0xf
	v_add_f32_dpp v135, v135, v135 row_half_mirror row_mask:0xf bank_mask:0xf
	v_add_f32_dpp v137, v137, v137 row_half_mirror row_mask:0xf bank_mask:0xf
	v_add_f32_dpp v131, v131, v131 row_mirror row_mask:0xf bank_mask:0xf
	v_add_f32_dpp v133, v133, v133 row_mirror row_mask:0xf bank_mask:0xf
	v_add_f32_dpp v135, v135, v135 row_mirror row_mask:0xf bank_mask:0xf
	v_add_f32_dpp v137, v137, v137 row_mirror row_mask:0xf bank_mask:0xf
	s_mov_b32 exec_lo, 0x10001
	s_mov_b32 exec_hi, 0x10001
	global_store_dwordx2 v1, v[130:131], s[18:19] offset:1024 sc1
	global_store_dwordx2 v1, v[132:133], s[18:19] offset:1280 sc1
	global_store_dwordx2 v1, v[134:135], s[18:19] offset:1536 sc1
	global_store_dwordx2 v1, v[136:137], s[18:19] offset:1792 sc1
	s_mov_b64 exec, -1
	s_waitcnt vmcnt(0)
	s_barrier
	v_readfirstlane_b32 s24, v0
	s_nop 3
	s_lshr_b32 s24, s24, 6
	s_cmp_lg_u32 s24, 0
	s_cbranch_scc1 .Lp17_w0_a
	v_mov_b32_e32 v182, 0
	v_mov_b32_e32 v183, 1
	s_mov_b64 exec, 1
	global_atomic_add v182, v183, s[22:23]
	s_mov_b64 exec, -1
.Lp17_w0_a:
	v_mov_b32_e32 v176, 0x3727c5ac
	v_and_b32_e32 v179, 48, v0
	v_lshlrev_b32_e32 v179, 2, v179
	v_add_f32_e32 v177, v238, v240
	v_add_f32_e32 v174, v242, v244
	v_add_f32_e32 v177, v177, v174
	v_mul_f32_e32 v177, 0x3e800000, v177
	v_sub_f32_e32 v238, v238, v177
	v_sub_f32_e32 v240, v240, v177
	v_sub_f32_e32 v242, v242, v177
	v_sub_f32_e32 v244, v244, v177
	v_mul_f32_e32 v174, v238, v238
	v_fmac_f32_e32 v174, v240, v240
	v_fmac_f32_e32 v174, v242, v242
	v_fmac_f32_e32 v174, v244, v244
	v_add_f32_e32 v239, v239, v241
	v_add_f32_e32 v243, v243, v245
	v_add_f32_e32 v239, v239, v243
	v_fmamk_f32 v174, v174, 0x43800000, v239
	v_fmamk_f32 v174, v174, 0x3a800000, v176
	v_rsq_f32_e32 v178, v174
	s_nop 0
	v_add_u32_e32 v180, 0, v179
	ds_bpermute_b32 v228, v180, v177
	ds_bpermute_b32 v229, v180, v178
	v_add_u32_e32 v181, 4, v179
	ds_bpermute_b32 v230, v181, v177
	ds_bpermute_b32 v231, v181, v178
	v_add_u32_e32 v180, 8, v179
	ds_bpermute_b32 v232, v180, v177
	ds_bpermute_b32 v233, v180, v178
	v_add_u32_e32 v181, 12, v179
	ds_bpermute_b32 v234, v181, v177
	ds_bpermute_b32 v235, v181, v178
	s_waitcnt lgkmcnt(0)
	v_readfirstlane_b32 s24, v0
	s_nop 3
	s_lshr_b32 s24, s24, 6
	s_cmp_lg_u32 s24, 0
	s_cbranch_scc1 .Lp17_others
	v_mov_b32_e32 v182, 0
	s_mov_b64 exec, 1
	s_mov_b32 s25, 0
.Lp17_pollB:
	global_load_dword v184, v182, s[22:23] sc1
	s_waitcnt vmcnt(0)
	v_readfirstlane_b32 s24, v184
	s_nop 3
	s_cmp_ge_u32 s24, 12
	s_cbranch_scc1 .Lp17_polledB
	s_sleep 1
	s_add_i32 s25, s25, 1
	s_cmp_lt_u32 s25, 0x4000
	s_cbranch_scc1 .Lp17_pollB
.Lp17_polledB:
	s_mov_b64 exec, -1
	s_branch .Lp17_join
.Lp17_others:
	s_mov_b32 s10, 0x0
	s_mov_b32 s11, 0
	v_lshl_add_u64 v[222:223], v[220:221], 0, s[10:11]
	v_pk_add_f32 v[98:99], v[98:99], v[228:229] op_sel_hi:[1,0] neg_lo:[0,1] neg_hi:[0,1]
	v_pk_mul_f32 v[98:99], v[98:99], v[228:229] op_sel:[0,1]
	v_pk_fma_f32 v[98:99], v[186:187], v[98:99], v[202:203]
	v_pk_add_f32 v[100:101], v[100:101], v[228:229] op_sel_hi:[1,0] neg_lo:[0,1] neg_hi:[0,1]
	v_pk_mul_f32 v[100:101], v[100:101], v[228:229] op_sel:[0,1]
	v_pk_fma_f32 v[100:101], v[188:189], v[100:101], v[204:205]
	v_pk_add_f32 v[102:103], v[102:103], v[228:229] op_sel_hi:[1,0] neg_lo:[0,1] neg_hi:[0,1]
	v_pk_mul_f32 v[102:103], v[102:103], v[228:229] op_sel:[0,1]
	v_pk_fma_f32 v[102:103], v[190:191], v[102:103], v[206:207]
	v_pk_add_f32 v[104:105], v[104:105], v[228:229] op_sel_hi:[1,0] neg_lo:[0,1] neg_hi:[0,1]
	v_pk_mul_f32 v[104:105], v[104:105], v[228:229] op_sel:[0,1]
	v_pk_fma_f32 v[104:105], v[192:193], v[104:105], v[208:209]
	global_store_dwordx4 v[222:223], v[98:101], off
	global_store_dwordx4 v[222:223], v[102:105], off offset:16
	s_mov_b32 s10, 0x20000
	s_mov_b32 s11, 0
	v_lshl_add_u64 v[218:219], v[220:221], 0, s[10:11]
	v_pk_add_f32 v[106:107], v[106:107], v[230:231] op_sel_hi:[1,0] neg_lo:[0,1] neg_hi:[0,1]
	v_pk_mul_f32 v[106:107], v[106:107], v[230:231] op_sel:[0,1]
	v_pk_fma_f32 v[106:107], v[186:187], v[106:107], v[202:203]
	v_pk_add_f32 v[108:109], v[108:109], v[230:231] op_sel_hi:[1,0] neg_lo:[0,1] neg_hi:[0,1]
	v_pk_mul_f32 v[108:109], v[108:109], v[230:231] op_sel:[0,1]
	v_pk_fma_f32 v[108:109], v[188:189], v[108:109], v[204:205]
	v_pk_add_f32 v[110:111], v[110:111], v[230:231] op_sel_hi:[1,0] neg_lo:[0,1] neg_hi:[0,1]
	v_pk_mul_f32 v[110:111], v[110:111], v[230:231] op_sel:[0,1]
	v_pk_fma_f32 v[110:111], v[190:191], v[110:111], v[206:207]
	v_pk_add_f32 v[112:113], v[112:113], v[230:231] op_sel_hi:[1,0] neg_lo:[0,1] neg_hi:[0,1]
	v_pk_mul_f32 v[112:113], v[112:113], v[230:231] op_sel:[0,1]
	v_pk_fma_f32 v[112:113], v[192:193], v[112:113], v[208:209]
	global_store_dwordx4 v[218:219], v[106:109], off
	global_store_dwordx4 v[218:219], v[110:113], off offset:16
	s_mov_b32 s10, 0x40000
	s_mov_b32 s11, 0
	v_lshl_add_u64 v[222:223], v[220:221], 0, s[10:11]
	v_pk_add_f32 v[114:115], v[114:115], v[232:233] op_sel_hi:[1,0] neg_lo:[0,1] neg_hi:[0,1]
	v_pk_mul_f32 v[114:115], v[114:115], v[232:233] op_sel:[0,1]
	v_pk_fma_f32 v[114:115], v[186:187], v[114:115], v[202:203]
	v_pk_add_f32 v[116:117], v[116:117], v[232:233] op_sel_hi:[1,0] neg_lo:[0,1] neg_hi:[0,1]
	v_pk_mul_f32 v[116:117], v[116:117], v[232:233] op_sel:[0,1]
	v_pk_fma_f32 v[116:117], v[188:189], v[116:117], v[204:205]
	v_pk_add_f32 v[118:119], v[118:119], v[232:233] op_sel_hi:[1,0] neg_lo:[0,1] neg_hi:[0,1]
	v_pk_mul_f32 v[118:119], v[118:119], v[232:233] op_sel:[0,1]
	v_pk_fma_f32 v[118:119], v[190:191], v[118:119], v[206:207]
	v_pk_add_f32 v[120:121], v[120:121], v[232:233] op_sel_hi:[1,0] neg_lo:[0,1] neg_hi:[0,1]
	v_pk_mul_f32 v[120:121], v[120:121], v[232:233] op_sel:[0,1]
	v_pk_fma_f32 v[120:121], v[192:193], v[120:121], v[208:209]
	global_store_dwordx4 v[222:223], v[114:117], off
	global_store_dwordx4 v[222:223], v[118:121], off offset:16
	s_mov_b32 s10, 0x60000
	s_mov_b32 s11, 0
	v_lshl_add_u64 v[218:219], v[220:221], 0, s[10:11]
	v_pk_add_f32 v[122:123], v[122:123], v[234:235] op_sel_hi:[1,0] neg_lo:[0,1] neg_hi:[0,1]
	v_pk_mul_f32 v[122:123], v[122:123], v[234:235] op_sel:[0,1]
	v_pk_fma_f32 v[122:123], v[186:187], v[122:123], v[202:203]
	v_pk_add_f32 v[124:125], v[124:125], v[234:235] op_sel_hi:[1,0] neg_lo:[0,1] neg_hi:[0,1]
	v_pk_mul_f32 v[124:125], v[124:125], v[234:235] op_sel:[0,1]
	v_pk_fma_f32 v[124:125], v[188:189], v[124:125], v[204:205]
	v_pk_add_f32 v[126:127], v[126:127], v[234:235] op_sel_hi:[1,0] neg_lo:[0,1] neg_hi:[0,1]
	v_pk_mul_f32 v[126:127], v[126:127], v[234:235] op_sel:[0,1]
	v_pk_fma_f32 v[126:127], v[190:191], v[126:127], v[206:207]
	v_pk_add_f32 v[128:129], v[128:129], v[234:235] op_sel_hi:[1,0] neg_lo:[0,1] neg_hi:[0,1]
	v_pk_mul_f32 v[128:129], v[128:129], v[234:235] op_sel:[0,1]
	v_pk_fma_f32 v[128:129], v[192:193], v[128:129], v[208:209]
	global_store_dwordx4 v[218:219], v[122:125], off
	global_store_dwordx4 v[218:219], v[126:129], off offset:16
	s_mov_b32 s10, 0x200
	s_mov_b32 s11, 0
	v_lshl_add_u64 v[222:223], v[220:221], 0, s[10:11]
	v_pk_add_f32 v[66:67], v[66:67], v[228:229] op_sel_hi:[1,0] neg_lo:[0,1] neg_hi:[0,1]
	v_pk_mul_f32 v[66:67], v[66:67], v[228:229] op_sel:[0,1]
	v_pk_fma_f32 v[66:67], v[194:195], v[66:67], v[210:211]
	v_pk_add_f32 v[68:69], v[68:69], v[228:229] op_sel_hi:[1,0] neg_lo:[0,1] neg_hi:[0,1]
	v_pk_mul_f32 v[68:69], v[68:69], v[228:229] op_sel:[0,1]
	v_pk_fma_f32 v[68:69], v[196:197], v[68:69], v[212:213]
	v_pk_add_f32 v[70:71], v[70:71], v[228:229] op_sel_hi:[1,0] neg_lo:[0,1] neg_hi:[0,1]
	v_pk_mul_f32 v[70:71], v[70:71], v[228:229] op_sel:[0,1]
	v_pk_fma_f32 v[70:71], v[198:199], v[70:71], v[214:215]
	v_pk_add_f32 v[72:73], v[72:73], v[228:229] op_sel_hi:[1,0] neg_lo:[0,1] neg_hi:[0,1]
	v_pk_mul_f32 v[72:73], v[72:73], v[228:229] op_sel:[0,1]
	v_pk_fma_f32 v[72:73], v[200:201], v[72:73], v[216:217]
	global_store_dwordx4 v[222:223], v[66:69], off
	global_store_dwordx4 v[222:223], v[70:73], off offset:16
	s_mov_b32 s10, 0x20200
	s_mov_b32 s11, 0
	v_lshl_add_u64 v[218:219], v[220:221], 0, s[10:11]
	v_pk_add_f32 v[74:75], v[74:75], v[230:231] op_sel_hi:[1,0] neg_lo:[0,1] neg_hi:[0,1]
	v_pk_mul_f32 v[74:75], v[74:75], v[230:231] op_sel:[0,1]
	v_pk_fma_f32 v[74:75], v[194:195], v[74:75], v[210:211]
	v_pk_add_f32 v[76:77], v[76:77], v[230:231] op_sel_hi:[1,0] neg_lo:[0,1] neg_hi:[0,1]
	v_pk_mul_f32 v[76:77], v[76:77], v[230:231] op_sel:[0,1]
	v_pk_fma_f32 v[76:77], v[196:197], v[76:77], v[212:213]
	v_pk_add_f32 v[78:79], v[78:79], v[230:231] op_sel_hi:[1,0] neg_lo:[0,1] neg_hi:[0,1]
	v_pk_mul_f32 v[78:79], v[78:79], v[230:231] op_sel:[0,1]
	v_pk_fma_f32 v[78:79], v[198:199], v[78:79], v[214:215]
	v_pk_add_f32 v[80:81], v[80:81], v[230:231] op_sel_hi:[1,0] neg_lo:[0,1] neg_hi:[0,1]
	v_pk_mul_f32 v[80:81], v[80:81], v[230:231] op_sel:[0,1]
	v_pk_fma_f32 v[80:81], v[200:201], v[80:81], v[216:217]
	global_store_dwordx4 v[218:219], v[74:77], off
	global_store_dwordx4 v[218:219], v[78:81], off offset:16
	s_mov_b32 s10, 0x40200
	s_mov_b32 s11, 0
	v_lshl_add_u64 v[222:223], v[220:221], 0, s[10:11]
	v_pk_add_f32 v[82:83], v[82:83], v[232:233] op_sel_hi:[1,0] neg_lo:[0,1] neg_hi:[0,1]
	v_pk_mul_f32 v[82:83], v[82:83], v[232:233] op_sel:[0,1]
	v_pk_fma_f32 v[82:83], v[194:195], v[82:83], v[210:211]
	v_pk_add_f32 v[84:85], v[84:85], v[232:233] op_sel_hi:[1,0] neg_lo:[0,1] neg_hi:[0,1]
	v_pk_mul_f32 v[84:85], v[84:85], v[232:233] op_sel:[0,1]
	v_pk_fma_f32 v[84:85], v[196:197], v[84:85], v[212:213]
	v_pk_add_f32 v[86:87], v[86:87], v[232:233] op_sel_hi:[1,0] neg_lo:[0,1] neg_hi:[0,1]
	v_pk_mul_f32 v[86:87], v[86:87], v[232:233] op_sel:[0,1]
	v_pk_fma_f32 v[86:87], v[198:199], v[86:87], v[214:215]
	v_pk_add_f32 v[88:89], v[88:89], v[232:233] op_sel_hi:[1,0] neg_lo:[0,1] neg_hi:[0,1]
	v_pk_mul_f32 v[88:89], v[88:89], v[232:233] op_sel:[0,1]
	v_pk_fma_f32 v[88:89], v[200:201], v[88:89], v[216:217]
	global_store_dwordx4 v[222:223], v[82:85], off
	global_store_dwordx4 v[222:223], v[86:89], off offset:16
	s_mov_b32 s10, 0x60200
	s_mov_b32 s11, 0
	v_lshl_add_u64 v[218:219], v[220:221], 0, s[10:11]
	v_pk_add_f32 v[90:91], v[90:91], v[234:235] op_sel_hi:[1,0] neg_lo:[0,1] neg_hi:[0,1]
	v_pk_mul_f32 v[90:91], v[90:91], v[234:235] op_sel:[0,1]
	v_pk_fma_f32 v[90:91], v[194:195], v[90:91], v[210:211]
	v_pk_add_f32 v[92:93], v[92:93], v[234:235] op_sel_hi:[1,0] neg_lo:[0,1] neg_hi:[0,1]
	v_pk_mul_f32 v[92:93], v[92:93], v[234:235] op_sel:[0,1]
	v_pk_fma_f32 v[92:93], v[196:197], v[92:93], v[212:213]
	v_pk_add_f32 v[94:95], v[94:95], v[234:235] op_sel_hi:[1,0] neg_lo:[0,1] neg_hi:[0,1]
	v_pk_mul_f32 v[94:95], v[94:95], v[234:235] op_sel:[0,1]
	v_pk_fma_f32 v[94:95], v[198:199], v[94:95], v[214:215]
	v_pk_add_f32 v[96:97], v[96:97], v[234:235] op_sel_hi:[1,0] neg_lo:[0,1] neg_hi:[0,1]
	v_pk_mul_f32 v[96:97], v[96:97], v[234:235] op_sel:[0,1]
	v_pk_fma_f32 v[96:97], v[200:201], v[96:97], v[216:217]
	global_store_dwordx4 v[218:219], v[90:93], off
	global_store_dwordx4 v[218:219], v[94:97], off offset:16
.Lp17_join:
	s_barrier
	v_and_b32_e32 v174, 3, v0
	v_lshl_add_u32 v174, v174, 8, v149
	v_add_u32_e32 v174, 0x400, v174
	v_add_u32_e32 v175, 0x1000, v174
	global_load_dwordx2 v[246:247], v174, s[18:19] sc1
	global_load_dwordx2 v[248:249], v174, s[18:19] offset:2048 sc1
	global_load_dwordx2 v[250:251], v175, s[18:19] sc1
	global_load_dwordx2 v[236:237], v175, s[18:19] offset:2048 sc1
	v_readfirstlane_b32 s24, v0
	s_nop 3
	s_lshr_b32 s24, s24, 6
	s_cmp_lg_u32 s24, 0
	s_cbranch_scc1 .Lp17_w0_b
	s_mov_b32 s10, 0x0
	s_mov_b32 s11, 0
	v_lshl_add_u64 v[222:223], v[220:221], 0, s[10:11]
	v_pk_add_f32 v[98:99], v[98:99], v[228:229] op_sel_hi:[1,0] neg_lo:[0,1] neg_hi:[0,1]
	v_pk_mul_f32 v[98:99], v[98:99], v[228:229] op_sel:[0,1]
	v_pk_fma_f32 v[98:99], v[186:187], v[98:99], v[202:203]
	v_pk_add_f32 v[100:101], v[100:101], v[228:229] op_sel_hi:[1,0] neg_lo:[0,1] neg_hi:[0,1]
	v_pk_mul_f32 v[100:101], v[100:101], v[228:229] op_sel:[0,1]
	v_pk_fma_f32 v[100:101], v[188:189], v[100:101], v[204:205]
	v_pk_add_f32 v[102:103], v[102:103], v[228:229] op_sel_hi:[1,0] neg_lo:[0,1] neg_hi:[0,1]
	v_pk_mul_f32 v[102:103], v[102:103], v[228:229] op_sel:[0,1]
	v_pk_fma_f32 v[102:103], v[190:191], v[102:103], v[206:207]
	v_pk_add_f32 v[104:105], v[104:105], v[228:229] op_sel_hi:[1,0] neg_lo:[0,1] neg_hi:[0,1]
	v_pk_mul_f32 v[104:105], v[104:105], v[228:229] op_sel:[0,1]
	v_pk_fma_f32 v[104:105], v[192:193], v[104:105], v[208:209]
	global_store_dwordx4 v[222:223], v[98:101], off
	global_store_dwordx4 v[222:223], v[102:105], off offset:16
	s_mov_b32 s10, 0x20000
	s_mov_b32 s11, 0
	v_lshl_add_u64 v[218:219], v[220:221], 0, s[10:11]
	v_pk_add_f32 v[106:107], v[106:107], v[230:231] op_sel_hi:[1,0] neg_lo:[0,1] neg_hi:[0,1]
	v_pk_mul_f32 v[106:107], v[106:107], v[230:231] op_sel:[0,1]
	v_pk_fma_f32 v[106:107], v[186:187], v[106:107], v[202:203]
	v_pk_add_f32 v[108:109], v[108:109], v[230:231] op_sel_hi:[1,0] neg_lo:[0,1] neg_hi:[0,1]
	v_pk_mul_f32 v[108:109], v[108:109], v[230:231] op_sel:[0,1]
	v_pk_fma_f32 v[108:109], v[188:189], v[108:109], v[204:205]
	v_pk_add_f32 v[110:111], v[110:111], v[230:231] op_sel_hi:[1,0] neg_lo:[0,1] neg_hi:[0,1]
	v_pk_mul_f32 v[110:111], v[110:111], v[230:231] op_sel:[0,1]
	v_pk_fma_f32 v[110:111], v[190:191], v[110:111], v[206:207]
	v_pk_add_f32 v[112:113], v[112:113], v[230:231] op_sel_hi:[1,0] neg_lo:[0,1] neg_hi:[0,1]
	v_pk_mul_f32 v[112:113], v[112:113], v[230:231] op_sel:[0,1]
	v_pk_fma_f32 v[112:113], v[192:193], v[112:113], v[208:209]
	global_store_dwordx4 v[218:219], v[106:109], off
	global_store_dwordx4 v[218:219], v[110:113], off offset:16
	s_mov_b32 s10, 0x40000
	s_mov_b32 s11, 0
	v_lshl_add_u64 v[222:223], v[220:221], 0, s[10:11]
	v_pk_add_f32 v[114:115], v[114:115], v[232:233] op_sel_hi:[1,0] neg_lo:[0,1] neg_hi:[0,1]
	v_pk_mul_f32 v[114:115], v[114:115], v[232:233] op_sel:[0,1]
	v_pk_fma_f32 v[114:115], v[186:187], v[114:115], v[202:203]
	v_pk_add_f32 v[116:117], v[116:117], v[232:233] op_sel_hi:[1,0] neg_lo:[0,1] neg_hi:[0,1]
	v_pk_mul_f32 v[116:117], v[116:117], v[232:233] op_sel:[0,1]
	v_pk_fma_f32 v[116:117], v[188:189], v[116:117], v[204:205]
	v_pk_add_f32 v[118:119], v[118:119], v[232:233] op_sel_hi:[1,0] neg_lo:[0,1] neg_hi:[0,1]
	v_pk_mul_f32 v[118:119], v[118:119], v[232:233] op_sel:[0,1]
	v_pk_fma_f32 v[118:119], v[190:191], v[118:119], v[206:207]
	v_pk_add_f32 v[120:121], v[120:121], v[232:233] op_sel_hi:[1,0] neg_lo:[0,1] neg_hi:[0,1]
	v_pk_mul_f32 v[120:121], v[120:121], v[232:233] op_sel:[0,1]
	v_pk_fma_f32 v[120:121], v[192:193], v[120:121], v[208:209]
	global_store_dwordx4 v[222:223], v[114:117], off
	global_store_dwordx4 v[222:223], v[118:121], off offset:16
	s_mov_b32 s10, 0x60000
	s_mov_b32 s11, 0
	v_lshl_add_u64 v[218:219], v[220:221], 0, s[10:11]
	v_pk_add_f32 v[122:123], v[122:123], v[234:235] op_sel_hi:[1,0] neg_lo:[0,1] neg_hi:[0,1]
	v_pk_mul_f32 v[122:123], v[122:123], v[234:235] op_sel:[0,1]
	v_pk_fma_f32 v[122:123], v[186:187], v[122:123], v[202:203]
	v_pk_add_f32 v[124:125], v[124:125], v[234:235] op_sel_hi:[1,0] neg_lo:[0,1] neg_hi:[0,1]
	v_pk_mul_f32 v[124:125], v[124:125], v[234:235] op_sel:[0,1]
	v_pk_fma_f32 v[124:125], v[188:189], v[124:125], v[204:205]
	v_pk_add_f32 v[126:127], v[126:127], v[234:235] op_sel_hi:[1,0] neg_lo:[0,1] neg_hi:[0,1]
	v_pk_mul_f32 v[126:127], v[126:127], v[234:235] op_sel:[0,1]
	v_pk_fma_f32 v[126:127], v[190:191], v[126:127], v[206:207]
	v_pk_add_f32 v[128:129], v[128:129], v[234:235] op_sel_hi:[1,0] neg_lo:[0,1] neg_hi:[0,1]
	v_pk_mul_f32 v[128:129], v[128:129], v[234:235] op_sel:[0,1]
	v_pk_fma_f32 v[128:129], v[192:193], v[128:129], v[208:209]
	global_store_dwordx4 v[218:219], v[122:125], off
	global_store_dwordx4 v[218:219], v[126:129], off offset:16
	s_mov_b32 s10, 0x200
	s_mov_b32 s11, 0
	v_lshl_add_u64 v[222:223], v[220:221], 0, s[10:11]
	v_pk_add_f32 v[66:67], v[66:67], v[228:229] op_sel_hi:[1,0] neg_lo:[0,1] neg_hi:[0,1]
	v_pk_mul_f32 v[66:67], v[66:67], v[228:229] op_sel:[0,1]
	v_pk_fma_f32 v[66:67], v[194:195], v[66:67], v[210:211]
	v_pk_add_f32 v[68:69], v[68:69], v[228:229] op_sel_hi:[1,0] neg_lo:[0,1] neg_hi:[0,1]
	v_pk_mul_f32 v[68:69], v[68:69], v[228:229] op_sel:[0,1]
	v_pk_fma_f32 v[68:69], v[196:197], v[68:69], v[212:213]
	v_pk_add_f32 v[70:71], v[70:71], v[228:229] op_sel_hi:[1,0] neg_lo:[0,1] neg_hi:[0,1]
	v_pk_mul_f32 v[70:71], v[70:71], v[228:229] op_sel:[0,1]
	v_pk_fma_f32 v[70:71], v[198:199], v[70:71], v[214:215]
	v_pk_add_f32 v[72:73], v[72:73], v[228:229] op_sel_hi:[1,0] neg_lo:[0,1] neg_hi:[0,1]
	v_pk_mul_f32 v[72:73], v[72:73], v[228:229] op_sel:[0,1]
	v_pk_fma_f32 v[72:73], v[200:201], v[72:73], v[216:217]
	global_store_dwordx4 v[222:223], v[66:69], off
	global_store_dwordx4 v[222:223], v[70:73], off offset:16
	s_mov_b32 s10, 0x20200
	s_mov_b32 s11, 0
	v_lshl_add_u64 v[218:219], v[220:221], 0, s[10:11]
	v_pk_add_f32 v[74:75], v[74:75], v[230:231] op_sel_hi:[1,0] neg_lo:[0,1] neg_hi:[0,1]
	v_pk_mul_f32 v[74:75], v[74:75], v[230:231] op_sel:[0,1]
	v_pk_fma_f32 v[74:75], v[194:195], v[74:75], v[210:211]
	v_pk_add_f32 v[76:77], v[76:77], v[230:231] op_sel_hi:[1,0] neg_lo:[0,1] neg_hi:[0,1]
	v_pk_mul_f32 v[76:77], v[76:77], v[230:231] op_sel:[0,1]
	v_pk_fma_f32 v[76:77], v[196:197], v[76:77], v[212:213]
	v_pk_add_f32 v[78:79], v[78:79], v[230:231] op_sel_hi:[1,0] neg_lo:[0,1] neg_hi:[0,1]
	v_pk_mul_f32 v[78:79], v[78:79], v[230:231] op_sel:[0,1]
	v_pk_fma_f32 v[78:79], v[198:199], v[78:79], v[214:215]
	v_pk_add_f32 v[80:81], v[80:81], v[230:231] op_sel_hi:[1,0] neg_lo:[0,1] neg_hi:[0,1]
	v_pk_mul_f32 v[80:81], v[80:81], v[230:231] op_sel:[0,1]
	v_pk_fma_f32 v[80:81], v[200:201], v[80:81], v[216:217]
	global_store_dwordx4 v[218:219], v[74:77], off
	global_store_dwordx4 v[218:219], v[78:81], off offset:16
	s_mov_b32 s10, 0x40200
	s_mov_b32 s11, 0
	v_lshl_add_u64 v[222:223], v[220:221], 0, s[10:11]
	v_pk_add_f32 v[82:83], v[82:83], v[232:233] op_sel_hi:[1,0] neg_lo:[0,1] neg_hi:[0,1]
	v_pk_mul_f32 v[82:83], v[82:83], v[232:233] op_sel:[0,1]
	v_pk_fma_f32 v[82:83], v[194:195], v[82:83], v[210:211]
	v_pk_add_f32 v[84:85], v[84:85], v[232:233] op_sel_hi:[1,0] neg_lo:[0,1] neg_hi:[0,1]
	v_pk_mul_f32 v[84:85], v[84:85], v[232:233] op_sel:[0,1]
	v_pk_fma_f32 v[84:85], v[196:197], v[84:85], v[212:213]
	v_pk_add_f32 v[86:87], v[86:87], v[232:233] op_sel_hi:[1,0] neg_lo:[0,1] neg_hi:[0,1]
	v_pk_mul_f32 v[86:87], v[86:87], v[232:233] op_sel:[0,1]
	v_pk_fma_f32 v[86:87], v[198:199], v[86:87], v[214:215]
	v_pk_add_f32 v[88:89], v[88:89], v[232:233] op_sel_hi:[1,0] neg_lo:[0,1] neg_hi:[0,1]
	v_pk_mul_f32 v[88:89], v[88:89], v[232:233] op_sel:[0,1]
	v_pk_fma_f32 v[88:89], v[200:201], v[88:89], v[216:217]
	global_store_dwordx4 v[222:223], v[82:85], off
	global_store_dwordx4 v[222:223], v[86:89], off offset:16
	s_mov_b32 s10, 0x60200
	s_mov_b32 s11, 0
	v_lshl_add_u64 v[218:219], v[220:221], 0, s[10:11]
	v_pk_add_f32 v[90:91], v[90:91], v[234:235] op_sel_hi:[1,0] neg_lo:[0,1] neg_hi:[0,1]
	v_pk_mul_f32 v[90:91], v[90:91], v[234:235] op_sel:[0,1]
	v_pk_fma_f32 v[90:91], v[194:195], v[90:91], v[210:211]
	v_pk_add_f32 v[92:93], v[92:93], v[234:235] op_sel_hi:[1,0] neg_lo:[0,1] neg_hi:[0,1]
	v_pk_mul_f32 v[92:93], v[92:93], v[234:235] op_sel:[0,1]
	v_pk_fma_f32 v[92:93], v[196:197], v[92:93], v[212:213]
	v_pk_add_f32 v[94:95], v[94:95], v[234:235] op_sel_hi:[1,0] neg_lo:[0,1] neg_hi:[0,1]
	v_pk_mul_f32 v[94:95], v[94:95], v[234:235] op_sel:[0,1]
	v_pk_fma_f32 v[94:95], v[198:199], v[94:95], v[214:215]
	v_pk_add_f32 v[96:97], v[96:97], v[234:235] op_sel_hi:[1,0] neg_lo:[0,1] neg_hi:[0,1]
	v_pk_mul_f32 v[96:97], v[96:97], v[234:235] op_sel:[0,1]
	v_pk_fma_f32 v[96:97], v[200:201], v[96:97], v[216:217]
	global_store_dwordx4 v[218:219], v[90:93], off
	global_store_dwordx4 v[218:219], v[94:97], off offset:16
.Lp17_w0_b:
	s_waitcnt vmcnt(0)
	v_mov_b32_e32 v176, 0x3727c5ac
	v_and_b32_e32 v179, 48, v0
	v_lshlrev_b32_e32 v179, 2, v179
	v_add_f32_e32 v177, v246, v248
	v_add_f32_e32 v174, v250, v236
	v_add_f32_e32 v177, v177, v174
	v_mul_f32_e32 v177, 0x3e800000, v177
	v_sub_f32_e32 v246, v246, v177
	v_sub_f32_e32 v248, v248, v177
	v_sub_f32_e32 v250, v250, v177
	v_sub_f32_e32 v236, v236, v177
	v_mul_f32_e32 v174, v246, v246
	v_fmac_f32_e32 v174, v248, v248
	v_fmac_f32_e32 v174, v250, v250
	v_fmac_f32_e32 v174, v236, v236
	v_add_f32_e32 v247, v247, v249
	v_add_f32_e32 v251, v251, v237
	v_add_f32_e32 v247, v247, v251
	v_fmamk_f32 v174, v174, 0x43800000, v247
	v_fmamk_f32 v174, v174, 0x3a800000, v176
	v_rsq_f32_e32 v178, v174
	s_nop 0
	v_add_u32_e32 v180, 0, v179
	ds_bpermute_b32 v130, v180, v177
	ds_bpermute_b32 v131, v180, v178
	v_add_u32_e32 v181, 4, v179
	ds_bpermute_b32 v132, v181, v177
	ds_bpermute_b32 v133, v181, v178
	v_add_u32_e32 v180, 8, v179
	ds_bpermute_b32 v134, v180, v177
	ds_bpermute_b32 v135, v180, v178
	v_add_u32_e32 v181, 12, v179
	ds_bpermute_b32 v136, v181, v177
	ds_bpermute_b32 v137, v181, v178
	s_waitcnt lgkmcnt(0)
	s_mov_b32 s10, 0x80000
	s_mov_b32 s11, 0
	v_lshl_add_u64 v[222:223], v[220:221], 0, s[10:11]
	v_pk_add_f32 v[34:35], v[34:35], v[130:131] op_sel_hi:[1,0] neg_lo:[0,1] neg_hi:[0,1]
	v_pk_mul_f32 v[34:35], v[34:35], v[130:131] op_sel:[0,1]
	v_pk_fma_f32 v[34:35], v[186:187], v[34:35], v[202:203]
	v_pk_add_f32 v[36:37], v[36:37], v[130:131] op_sel_hi:[1,0] neg_lo:[0,1] neg_hi:[0,1]
	v_pk_mul_f32 v[36:37], v[36:37], v[130:131] op_sel:[0,1]
	v_pk_fma_f32 v[36:37], v[188:189], v[36:37], v[204:205]
	v_pk_add_f32 v[38:39], v[38:39], v[130:131] op_sel_hi:[1,0] neg_lo:[0,1] neg_hi:[0,1]
	v_pk_mul_f32 v[38:39], v[38:39], v[130:131] op_sel:[0,1]
	v_pk_fma_f32 v[38:39], v[190:191], v[38:39], v[206:207]
	v_pk_add_f32 v[40:41], v[40:41], v[130:131] op_sel_hi:[1,0] neg_lo:[0,1] neg_hi:[0,1]
	v_pk_mul_f32 v[40:41], v[40:41], v[130:131] op_sel:[0,1]
	v_pk_fma_f32 v[40:41], v[192:193], v[40:41], v[208:209]
	global_store_dwordx4 v[222:223], v[34:37], off
	global_store_dwordx4 v[222:223], v[38:41], off offset:16
	s_mov_b32 s10, 0xa0000
	s_mov_b32 s11, 0
	v_lshl_add_u64 v[218:219], v[220:221], 0, s[10:11]
	v_pk_add_f32 v[42:43], v[42:43], v[132:133] op_sel_hi:[1,0] neg_lo:[0,1] neg_hi:[0,1]
	v_pk_mul_f32 v[42:43], v[42:43], v[132:133] op_sel:[0,1]
	v_pk_fma_f32 v[42:43], v[186:187], v[42:43], v[202:203]
	v_pk_add_f32 v[44:45], v[44:45], v[132:133] op_sel_hi:[1,0] neg_lo:[0,1] neg_hi:[0,1]
	v_pk_mul_f32 v[44:45], v[44:45], v[132:133] op_sel:[0,1]
	v_pk_fma_f32 v[44:45], v[188:189], v[44:45], v[204:205]
	v_pk_add_f32 v[46:47], v[46:47], v[132:133] op_sel_hi:[1,0] neg_lo:[0,1] neg_hi:[0,1]
	v_pk_mul_f32 v[46:47], v[46:47], v[132:133] op_sel:[0,1]
	v_pk_fma_f32 v[46:47], v[190:191], v[46:47], v[206:207]
	v_pk_add_f32 v[48:49], v[48:49], v[132:133] op_sel_hi:[1,0] neg_lo:[0,1] neg_hi:[0,1]
	v_pk_mul_f32 v[48:49], v[48:49], v[132:133] op_sel:[0,1]
	v_pk_fma_f32 v[48:49], v[192:193], v[48:49], v[208:209]
	global_store_dwordx4 v[218:219], v[42:45], off
	global_store_dwordx4 v[218:219], v[46:49], off offset:16
	s_mov_b32 s10, 0xc0000
	s_mov_b32 s11, 0
	v_lshl_add_u64 v[222:223], v[220:221], 0, s[10:11]
	v_pk_add_f32 v[50:51], v[50:51], v[134:135] op_sel_hi:[1,0] neg_lo:[0,1] neg_hi:[0,1]
	v_pk_mul_f32 v[50:51], v[50:51], v[134:135] op_sel:[0,1]
	v_pk_fma_f32 v[50:51], v[186:187], v[50:51], v[202:203]
	v_pk_add_f32 v[52:53], v[52:53], v[134:135] op_sel_hi:[1,0] neg_lo:[0,1] neg_hi:[0,1]
	v_pk_mul_f32 v[52:53], v[52:53], v[134:135] op_sel:[0,1]
	v_pk_fma_f32 v[52:53], v[188:189], v[52:53], v[204:205]
	v_pk_add_f32 v[54:55], v[54:55], v[134:135] op_sel_hi:[1,0] neg_lo:[0,1] neg_hi:[0,1]
	v_pk_mul_f32 v[54:55], v[54:55], v[134:135] op_sel:[0,1]
	v_pk_fma_f32 v[54:55], v[190:191], v[54:55], v[206:207]
	v_pk_add_f32 v[56:57], v[56:57], v[134:135] op_sel_hi:[1,0] neg_lo:[0,1] neg_hi:[0,1]
	v_pk_mul_f32 v[56:57], v[56:57], v[134:135] op_sel:[0,1]
	v_pk_fma_f32 v[56:57], v[192:193], v[56:57], v[208:209]
	global_store_dwordx4 v[222:223], v[50:53], off
	global_store_dwordx4 v[222:223], v[54:57], off offset:16
	s_mov_b32 s10, 0xe0000
	s_mov_b32 s11, 0
	v_lshl_add_u64 v[218:219], v[220:221], 0, s[10:11]
	v_pk_add_f32 v[58:59], v[58:59], v[136:137] op_sel_hi:[1,0] neg_lo:[0,1] neg_hi:[0,1]
	v_pk_mul_f32 v[58:59], v[58:59], v[136:137] op_sel:[0,1]
	v_pk_fma_f32 v[58:59], v[186:187], v[58:59], v[202:203]
	v_pk_add_f32 v[60:61], v[60:61], v[136:137] op_sel_hi:[1,0] neg_lo:[0,1] neg_hi:[0,1]
	v_pk_mul_f32 v[60:61], v[60:61], v[136:137] op_sel:[0,1]
	v_pk_fma_f32 v[60:61], v[188:189], v[60:61], v[204:205]
	v_pk_add_f32 v[62:63], v[62:63], v[136:137] op_sel_hi:[1,0] neg_lo:[0,1] neg_hi:[0,1]
	v_pk_mul_f32 v[62:63], v[62:63], v[136:137] op_sel:[0,1]
	v_pk_fma_f32 v[62:63], v[190:191], v[62:63], v[206:207]
	v_pk_add_f32 v[64:65], v[64:65], v[136:137] op_sel_hi:[1,0] neg_lo:[0,1] neg_hi:[0,1]
	v_pk_mul_f32 v[64:65], v[64:65], v[136:137] op_sel:[0,1]
	v_pk_fma_f32 v[64:65], v[192:193], v[64:65], v[208:209]
	global_store_dwordx4 v[218:219], v[58:61], off
	global_store_dwordx4 v[218:219], v[62:65], off offset:16
	s_mov_b32 s10, 0x80200
	s_mov_b32 s11, 0
	v_lshl_add_u64 v[222:223], v[220:221], 0, s[10:11]
	v_pk_add_f32 v[2:3], v[2:3], v[130:131] op_sel_hi:[1,0] neg_lo:[0,1] neg_hi:[0,1]
	v_pk_mul_f32 v[2:3], v[2:3], v[130:131] op_sel:[0,1]
	v_pk_fma_f32 v[2:3], v[194:195], v[2:3], v[210:211]
	v_pk_add_f32 v[4:5], v[4:5], v[130:131] op_sel_hi:[1,0] neg_lo:[0,1] neg_hi:[0,1]
	v_pk_mul_f32 v[4:5], v[4:5], v[130:131] op_sel:[0,1]
	v_pk_fma_f32 v[4:5], v[196:197], v[4:5], v[212:213]
	v_pk_add_f32 v[6:7], v[6:7], v[130:131] op_sel_hi:[1,0] neg_lo:[0,1] neg_hi:[0,1]
	v_pk_mul_f32 v[6:7], v[6:7], v[130:131] op_sel:[0,1]
	v_pk_fma_f32 v[6:7], v[198:199], v[6:7], v[214:215]
	v_pk_add_f32 v[8:9], v[8:9], v[130:131] op_sel_hi:[1,0] neg_lo:[0,1] neg_hi:[0,1]
	v_pk_mul_f32 v[8:9], v[8:9], v[130:131] op_sel:[0,1]
	v_pk_fma_f32 v[8:9], v[200:201], v[8:9], v[216:217]
	global_store_dwordx4 v[222:223], v[2:5], off
	global_store_dwordx4 v[222:223], v[6:9], off offset:16
	s_mov_b32 s10, 0xa0200
	s_mov_b32 s11, 0
	v_lshl_add_u64 v[218:219], v[220:221], 0, s[10:11]
	v_pk_add_f32 v[10:11], v[10:11], v[132:133] op_sel_hi:[1,0] neg_lo:[0,1] neg_hi:[0,1]
	v_pk_mul_f32 v[10:11], v[10:11], v[132:133] op_sel:[0,1]
	v_pk_fma_f32 v[10:11], v[194:195], v[10:11], v[210:211]
	v_pk_add_f32 v[12:13], v[12:13], v[132:133] op_sel_hi:[1,0] neg_lo:[0,1] neg_hi:[0,1]
	v_pk_mul_f32 v[12:13], v[12:13], v[132:133] op_sel:[0,1]
	v_pk_fma_f32 v[12:13], v[196:197], v[12:13], v[212:213]
	v_pk_add_f32 v[14:15], v[14:15], v[132:133] op_sel_hi:[1,0] neg_lo:[0,1] neg_hi:[0,1]
	v_pk_mul_f32 v[14:15], v[14:15], v[132:133] op_sel:[0,1]
	v_pk_fma_f32 v[14:15], v[198:199], v[14:15], v[214:215]
	v_pk_add_f32 v[16:17], v[16:17], v[132:133] op_sel_hi:[1,0] neg_lo:[0,1] neg_hi:[0,1]
	v_pk_mul_f32 v[16:17], v[16:17], v[132:133] op_sel:[0,1]
	v_pk_fma_f32 v[16:17], v[200:201], v[16:17], v[216:217]
	global_store_dwordx4 v[218:219], v[10:13], off
	global_store_dwordx4 v[218:219], v[14:17], off offset:16
	s_mov_b32 s10, 0xc0200
	s_mov_b32 s11, 0
	v_lshl_add_u64 v[222:223], v[220:221], 0, s[10:11]
	v_pk_add_f32 v[18:19], v[18:19], v[134:135] op_sel_hi:[1,0] neg_lo:[0,1] neg_hi:[0,1]
	v_pk_mul_f32 v[18:19], v[18:19], v[134:135] op_sel:[0,1]
	v_pk_fma_f32 v[18:19], v[194:195], v[18:19], v[210:211]
	v_pk_add_f32 v[20:21], v[20:21], v[134:135] op_sel_hi:[1,0] neg_lo:[0,1] neg_hi:[0,1]
	v_pk_mul_f32 v[20:21], v[20:21], v[134:135] op_sel:[0,1]
	v_pk_fma_f32 v[20:21], v[196:197], v[20:21], v[212:213]
	v_pk_add_f32 v[22:23], v[22:23], v[134:135] op_sel_hi:[1,0] neg_lo:[0,1] neg_hi:[0,1]
	v_pk_mul_f32 v[22:23], v[22:23], v[134:135] op_sel:[0,1]
	v_pk_fma_f32 v[22:23], v[198:199], v[22:23], v[214:215]
	v_pk_add_f32 v[24:25], v[24:25], v[134:135] op_sel_hi:[1,0] neg_lo:[0,1] neg_hi:[0,1]
	v_pk_mul_f32 v[24:25], v[24:25], v[134:135] op_sel:[0,1]
	v_pk_fma_f32 v[24:25], v[200:201], v[24:25], v[216:217]
	global_store_dwordx4 v[222:223], v[18:21], off
	global_store_dwordx4 v[222:223], v[22:25], off offset:16
	s_mov_b32 s10, 0xe0200
	s_mov_b32 s11, 0
	v_lshl_add_u64 v[218:219], v[220:221], 0, s[10:11]
	v_pk_add_f32 v[26:27], v[26:27], v[136:137] op_sel_hi:[1,0] neg_lo:[0,1] neg_hi:[0,1]
	v_pk_mul_f32 v[26:27], v[26:27], v[136:137] op_sel:[0,1]
	v_pk_fma_f32 v[26:27], v[194:195], v[26:27], v[210:211]
	v_pk_add_f32 v[28:29], v[28:29], v[136:137] op_sel_hi:[1,0] neg_lo:[0,1] neg_hi:[0,1]
	v_pk_mul_f32 v[28:29], v[28:29], v[136:137] op_sel:[0,1]
	v_pk_fma_f32 v[28:29], v[196:197], v[28:29], v[212:213]
	v_pk_add_f32 v[30:31], v[30:31], v[136:137] op_sel_hi:[1,0] neg_lo:[0,1] neg_hi:[0,1]
	v_pk_mul_f32 v[30:31], v[30:31], v[136:137] op_sel:[0,1]
	v_pk_fma_f32 v[30:31], v[198:199], v[30:31], v[214:215]
	v_pk_add_f32 v[32:33], v[32:33], v[136:137] op_sel_hi:[1,0] neg_lo:[0,1] neg_hi:[0,1]
	v_pk_mul_f32 v[32:33], v[32:33], v[136:137] op_sel:[0,1]
	v_pk_fma_f32 v[32:33], v[200:201], v[32:33], v[216:217]
	global_store_dwordx4 v[218:219], v[26:29], off
	global_store_dwordx4 v[218:219], v[30:33], off offset:16
	s_endpgm
